# attention: dropped compiler over-conservative vmcnt waits at the start of QK (K/V prefetch now overlaps the tile compute), on top of the mixer recurrence restructure
# speedup vs baseline: 1.0027x; 1.0008x over previous
; #define LAS __attribute__((address_space(3)))
; __device__ __forceinline__ f32x4 mfma16(bf16x8 a, bf16x8 b, f32x4 c) { return __builtin_amdgcn_mfma_f32_16x16x32_bf16(a, b, c, 0, 0, 0); }
; template <bool DIAG, int NST>
; __device__ __forceinline__ void attn_tile(LAS unsigned char* lds, const bf16x8 (&qf)[4], f32x4 (&accO)[8], float& R, int w, int l15, int quad, int tl, bf16x8 U1, bf16x8 T0, bf16x8 T1) {
;     ...
;     f32x4 z[8];
; #pragma unroll
;     for (int st = 0; st < NST; ++st) { z[st] = (f32x4){0.f, 0.f, 0.f, 0.f};
;         if (true) {
; #pragma unroll
;             for (int ks = 0; ks < 4; ++ks) { const bf16x8 a = *(const LAS bf16x8*)(lds + AT_KS + (16 * st + l15) * 272 + (32 * ks + 8 * quad) * 2); z[st] = mfma16(a, qf[ks], z[st]); } }
;         if (st & 1) __builtin_amdgcn_sched_barrier(0); }
;     float rs = 0.f;
; #pragma unroll
;     for (int st = 0; st < NST; ++st) {
;         u32x2 wv = {0u, 0u};
;         if (true) { float lk[4];
; #pragma unroll
;             for (int j = 0; j < 4; ++j) { const float z2 = z[st][j] * SCALE2; float sp = __builtin_amdgcn_logf(1.0f + __builtin_amdgcn_exp2f(z2)); sp = (z2 > 64.0f) ? z2 : sp;
;                 if (DIAG) { const int s = 16 * st + 4 * quad + j; lk[j] = (s < tl) ? -sp : 0.f; } else lk[j] = -sp;
;                 z[st][j] = z2 - sp; rs += lk[j]; }
.LBB0_984:
	ds_read_b128 v[88:91], v173
	s_cmp_lg_u32 s96, 0
	s_cselect_b64 s[90:91], -1, 0
	s_cmp_eq_u32 s96, 0
	v_add_u32_e32 v167, v174, v159
	s_cbranch_scc1 .LBB0_986
	ds_read_b128 v[96:99], v173 offset:64
	s_waitcnt lgkmcnt(1)
	v_mfma_f32_16x16x32_bf16 v[92:95], v[88:91], v[24:27], 0
	s_waitcnt lgkmcnt(0)
	v_mfma_f32_16x16x32_bf16 v[92:95], v[96:99], v[28:31], v[92:95]
	ds_read_b128 v[96:99], v173 offset:128
	s_waitcnt lgkmcnt(0)
	v_mfma_f32_16x16x32_bf16 v[92:95], v[96:99], v[32:35], v[92:95]
	ds_read_b128 v[96:99], v173 offset:192
	s_waitcnt lgkmcnt(0)
	v_mfma_f32_16x16x32_bf16 v[120:123], v[96:99], v[36:39], v[92:95]
	s_nop 4
	ds_read_b128 v[92:95], v173 offset:4352
	ds_read_b128 v[96:99], v173 offset:4416
	s_waitcnt lgkmcnt(1)
	v_mfma_f32_16x16x32_bf16 v[92:95], v[92:95], v[24:27], 0
	s_waitcnt lgkmcnt(0)
	v_mfma_f32_16x16x32_bf16 v[92:95], v[96:99], v[28:31], v[92:95]
	ds_read_b128 v[96:99], v173 offset:4480
	s_waitcnt lgkmcnt(0)
	v_mfma_f32_16x16x32_bf16 v[92:95], v[96:99], v[32:35], v[92:95]
	ds_read_b128 v[96:99], v173 offset:4544
	s_waitcnt lgkmcnt(0)
	v_mfma_f32_16x16x32_bf16 v[116:119], v[96:99], v[36:39], v[92:95]
	s_nop 4
	ds_read_b128 v[92:95], v173 offset:8704
	ds_read_b128 v[96:99], v173 offset:8768
	s_waitcnt lgkmcnt(1)
	v_mfma_f32_16x16x32_bf16 v[92:95], v[92:95], v[24:27], 0
	s_waitcnt lgkmcnt(0)
	v_mfma_f32_16x16x32_bf16 v[92:95], v[96:99], v[28:31], v[92:95]
	ds_read_b128 v[96:99], v173 offset:8832
	s_waitcnt lgkmcnt(0)
	v_mfma_f32_16x16x32_bf16 v[92:95], v[96:99], v[32:35], v[92:95]
	ds_read_b128 v[96:99], v173 offset:8896
	s_waitcnt lgkmcnt(0)
	v_mfma_f32_16x16x32_bf16 v[108:111], v[96:99], v[36:39], v[92:95]
	s_nop 4
	ds_read_b128 v[92:95], v173 offset:13056
	ds_read_b128 v[96:99], v173 offset:13120
	s_waitcnt lgkmcnt(1)
	v_mfma_f32_16x16x32_bf16 v[92:95], v[92:95], v[24:27], 0
	s_waitcnt lgkmcnt(0)
	v_mfma_f32_16x16x32_bf16 v[92:95], v[96:99], v[28:31], v[92:95]
	ds_read_b128 v[96:99], v173 offset:13184
	s_waitcnt lgkmcnt(0)
	v_mfma_f32_16x16x32_bf16 v[92:95], v[96:99], v[32:35], v[92:95]
	ds_read_b128 v[96:99], v173 offset:13248
	s_waitcnt lgkmcnt(0)
	v_mfma_f32_16x16x32_bf16 v[112:115], v[96:99], v[36:39], v[92:95]
	s_nop 4
	ds_read_b128 v[92:95], v173 offset:17408
	ds_read_b128 v[96:99], v173 offset:17472
	s_waitcnt lgkmcnt(1)
	v_mfma_f32_16x16x32_bf16 v[92:95], v[92:95], v[24:27], 0
	s_waitcnt lgkmcnt(0)
	v_mfma_f32_16x16x32_bf16 v[92:95], v[96:99], v[28:31], v[92:95]
	ds_read_b128 v[96:99], v173 offset:17536
	s_waitcnt lgkmcnt(0)
	v_mfma_f32_16x16x32_bf16 v[92:95], v[96:99], v[32:35], v[92:95]
	ds_read_b128 v[96:99], v173 offset:17600
	s_waitcnt lgkmcnt(0)
	v_mfma_f32_16x16x32_bf16 v[100:103], v[96:99], v[36:39], v[92:95]
	s_nop 4
	ds_read_b128 v[92:95], v173 offset:21760
	ds_read_b128 v[96:99], v173 offset:21824
	s_waitcnt lgkmcnt(1)
	v_mfma_f32_16x16x32_bf16 v[92:95], v[92:95], v[24:27], 0
	s_waitcnt lgkmcnt(0)
	v_mfma_f32_16x16x32_bf16 v[92:95], v[96:99], v[28:31], v[92:95]
	ds_read_b128 v[96:99], v173 offset:21888
	s_waitcnt lgkmcnt(0)
	v_mfma_f32_16x16x32_bf16 v[92:95], v[96:99], v[32:35], v[92:95]
	ds_read_b128 v[96:99], v173 offset:21952
	s_waitcnt lgkmcnt(0)
	v_mfma_f32_16x16x32_bf16 v[104:107], v[96:99], v[36:39], v[92:95]
	s_nop 4
	ds_read_b128 v[92:95], v173 offset:26112
	ds_read_b128 v[96:99], v173 offset:26176
	s_waitcnt lgkmcnt(1)
	v_mfma_f32_16x16x32_bf16 v[92:95], v[92:95], v[24:27], 0
	ds_read_b128 v[124:127], v173 offset:30528
	s_waitcnt lgkmcnt(1)
	v_mfma_f32_16x16x32_bf16 v[92:95], v[96:99], v[28:31], v[92:95]
	ds_read_b128 v[96:99], v173 offset:26240
	s_waitcnt lgkmcnt(0)
	v_mfma_f32_16x16x32_bf16 v[92:95], v[96:99], v[32:35], v[92:95]
	ds_read_b128 v[96:99], v173 offset:26304
	s_waitcnt lgkmcnt(0)
	v_mfma_f32_16x16x32_bf16 v[96:99], v[96:99], v[36:39], v[92:95]
	s_nop 4
	ds_read_b128 v[92:95], v173 offset:30464
	s_waitcnt lgkmcnt(0)
	v_mfma_f32_16x16x32_bf16 v[92:95], v[92:95], v[24:27], 0
	v_mfma_f32_16x16x32_bf16 v[92:95], v[124:127], v[28:31], v[92:95]
	ds_read_b128 v[124:127], v173 offset:30592
	s_waitcnt lgkmcnt(0)
	v_mfma_f32_16x16x32_bf16 v[92:95], v[124:127], v[32:35], v[92:95]
	ds_read_b128 v[124:127], v173 offset:30656
	s_waitcnt lgkmcnt(0)
	v_mfma_f32_16x16x32_bf16 v[92:95], v[124:127], v[36:39], v[92:95]
	v_mul_f32_e64 v124, v120, s88
	v_mul_f32_e64 v125, v121, s88
	v_pk_mul_f32 v[126:127], v[122:123], s[88:89] op_sel_hi:[1,0]
	v_exp_f32_e32 v128, v125
	v_exp_f32_e32 v129, v124
	v_exp_f32_e32 v130, v127
	v_cmp_lt_f32_e32 vcc, s5, v125
	v_add_f32_e32 v128, 1.0, v128
	v_log_f32_e32 v128, v128
	v_add_f32_e32 v129, 1.0, v129
	v_log_f32_e32 v129, v129
	v_cndmask_b32_e32 v125, v128, v125, vcc
	v_exp_f32_e32 v128, v126
	v_cmp_lt_f32_e32 vcc, s5, v124
	v_add_f32_e32 v128, 1.0, v128
	s_nop 0
	v_cndmask_b32_e32 v124, v129, v124, vcc
	v_add_f32_e32 v129, 1.0, v130
	v_log_f32_e32 v129, v129
	v_log_f32_e32 v128, v128
	v_cmp_lt_f32_e32 vcc, s5, v127
	v_pk_fma_f32 v[120:121], v[120:121], s[88:89], v[124:125] op_sel_hi:[1,0,1] neg_lo:[0,0,1] neg_hi:[0,0,1]
	s_nop 0
	v_cndmask_b32_e32 v129, v129, v127, vcc
	v_cmp_lt_f32_e32 vcc, s5, v126
	s_nop 1
	v_cndmask_b32_e32 v128, v128, v126, vcc
	v_pk_add_f32 v[126:127], v[124:125], 0 neg_lo:[1,1] neg_hi:[1,1]
	v_pk_fma_f32 v[122:123], v[122:123], s[88:89], v[128:129] op_sel_hi:[1,0,1] neg_lo:[0,0,1] neg_hi:[0,0,1]
	v_cvt_pk_bf16_f32 v130, v126, v127
	v_pk_add_f32 v[126:127], v[128:129], 0 neg_lo:[1,1] neg_hi:[1,1]
	s_nop 0
	v_cvt_pk_bf16_f32 v131, v126, v127
	v_sub_f32_e64 v127, -v124, v125
	v_pk_mul_f32 v[124:125], v[116:117], s[88:89] op_sel_hi:[1,0]
	v_sub_f32_e32 v127, v127, v128
	v_exp_f32_e32 v132, v125
	v_exp_f32_e32 v128, v124
; #define LAS __attribute__((address_space(3)))
; __device__ __forceinline__ unsigned pk2(float lo, float hi) { return pg8::cvt_pk_bf16(lo, hi); }
; template <bool DIAG, int NST>
; __device__ __forceinline__ void attn_tile(LAS unsigned char* lds, const bf16x8 (&qf)[4], f32x4 (&accO)[8], float& R, int w, int l15, int quad, int tl, bf16x8 U1, bf16x8 T0, bf16x8 T1) {
;     ...
;     float rs = 0.f;
; #pragma unroll
;     for (int st = 0; st < NST; ++st) {
;         u32x2 wv = {0u, 0u};
;         if (true) { float lk[4];
; #pragma unroll
;             for (int j = 0; j < 4; ++j) { const float z2 = z[st][j] * SCALE2; float sp = __builtin_amdgcn_logf(1.0f + __builtin_amdgcn_exp2f(z2)); sp = (z2 > 64.0f) ? z2 : sp;
;                 if (DIAG) { const int s = 16 * st + 4 * quad + j; lk[j] = (s < tl) ? -sp : 0.f; } else lk[j] = -sp;
;                 z[st][j] = z2 - sp; rs += lk[j]; }
;             wv.x = pk2(lk[0], lk[1]); wv.y = pk2(lk[2], lk[3]); }
;         *(LAS u32x2*)(lds + AT_P + tl * 272 + (16 * st + 4 * quad) * 2) = wv;
;         if (st & 1) __builtin_amdgcn_sched_barrier(0); }
	v_sub_f32_e32 v127, v127, v129
	v_cmp_lt_f32_e32 vcc, s5, v125
	v_add_f32_e32 v129, 1.0, v132
	v_log_f32_e32 v129, v129
	v_add_f32_e32 v128, 1.0, v128
	v_log_f32_e32 v128, v128
	v_add_u32_e32 v126, v174, v158
	v_cndmask_b32_e32 v125, v129, v125, vcc
	v_cmp_lt_f32_e32 vcc, s5, v124
	s_nop 1
	v_cndmask_b32_e32 v124, v128, v124, vcc
	v_pk_mul_f32 v[128:129], v[118:119], s[88:89] op_sel_hi:[1,0]
	v_sub_f32_e32 v127, v127, v124
	v_exp_f32_e32 v132, v129
	v_exp_f32_e32 v133, v128
	v_cmp_lt_f32_e32 vcc, s5, v129
	v_sub_f32_e32 v127, v127, v125
	v_add_f32_e32 v132, 1.0, v132
	v_log_f32_e32 v132, v132
	v_add_f32_e32 v133, 1.0, v133
	v_log_f32_e32 v133, v133
	v_pk_fma_f32 v[116:117], v[116:117], s[88:89], v[124:125] op_sel_hi:[1,0,1] neg_lo:[0,0,1] neg_hi:[0,0,1]
	v_cndmask_b32_e32 v129, v132, v129, vcc
	v_cmp_lt_f32_e32 vcc, s5, v128
	v_pk_add_f32 v[124:125], v[124:125], 0 neg_lo:[1,1] neg_hi:[1,1]
	s_nop 0
	v_cndmask_b32_e32 v128, v133, v128, vcc
	v_sub_f32_e32 v127, v127, v128
	v_pk_fma_f32 v[118:119], v[118:119], s[88:89], v[128:129] op_sel_hi:[1,0,1] neg_lo:[0,0,1] neg_hi:[0,0,1]
	v_sub_f32_e32 v127, v127, v129
	v_pk_add_f32 v[128:129], v[128:129], 0 neg_lo:[1,1] neg_hi:[1,1]
	v_cvt_pk_bf16_f32 v124, v124, v125
	v_cvt_pk_bf16_f32 v125, v128, v129
	ds_write2_b64 v126, v[130:131], v[124:125] offset1:4
	v_pk_mul_f32 v[124:125], v[108:109], s[88:89] op_sel_hi:[1,0]
	v_pk_mul_f32 v[128:129], v[110:111], s[88:89] op_sel_hi:[1,0]
	v_exp_f32_e32 v130, v125
	v_exp_f32_e32 v131, v124
	v_cmp_lt_f32_e32 vcc, s5, v125
	v_exp_f32_e32 v132, v129
	v_add_f32_e32 v130, 1.0, v130
	v_log_f32_e32 v130, v130
	v_add_f32_e32 v131, 1.0, v131
	v_log_f32_e32 v133, v131
	v_cndmask_b32_e32 v131, v130, v125, vcc
	v_cmp_lt_f32_e32 vcc, s5, v124
	s_nop 1
	v_cndmask_b32_e32 v130, v133, v124, vcc
	v_exp_f32_e32 v133, v128
	v_pk_fma_f32 v[124:125], v[108:109], s[88:89], v[130:131] op_sel_hi:[1,0,1] neg_lo:[0,0,1] neg_hi:[0,0,1]
	v_add_f32_e32 v108, 1.0, v132
	v_log_f32_e32 v108, v108
	v_add_f32_e32 v109, 1.0, v133
	v_log_f32_e32 v109, v109
	v_cmp_lt_f32_e32 vcc, s5, v129
	s_nop 1
	v_cndmask_b32_e32 v129, v108, v129, vcc
	v_cmp_lt_f32_e32 vcc, s5, v128
	s_nop 1
	v_cndmask_b32_e32 v128, v109, v128, vcc
	v_pk_fma_f32 v[108:109], v[110:111], s[88:89], v[128:129] op_sel_hi:[1,0,1] neg_lo:[0,0,1] neg_hi:[0,0,1]
	v_pk_add_f32 v[110:111], v[130:131], 0 neg_lo:[1,1] neg_hi:[1,1]
	s_nop 0
	v_cvt_pk_bf16_f32 v132, v110, v111
	v_pk_add_f32 v[110:111], v[128:129], 0 neg_lo:[1,1] neg_hi:[1,1]
	s_nop 0
	v_cvt_pk_bf16_f32 v133, v110, v111
	v_sub_f32_e32 v110, v127, v130
	v_sub_f32_e32 v127, v110, v131
	v_pk_mul_f32 v[110:111], v[112:113], s[88:89] op_sel_hi:[1,0]
	v_sub_f32_e32 v127, v127, v128
	v_exp_f32_e32 v130, v111
	v_exp_f32_e32 v128, v110
	v_sub_f32_e32 v127, v127, v129
	v_cmp_lt_f32_e32 vcc, s5, v111
	v_add_f32_e32 v129, 1.0, v130
	v_log_f32_e32 v129, v129
	v_add_f32_e32 v128, 1.0, v128
	v_log_f32_e32 v128, v128
	v_cndmask_b32_e32 v129, v129, v111, vcc
	v_cmp_lt_f32_e32 vcc, s5, v110
	s_nop 1
	v_cndmask_b32_e32 v128, v128, v110, vcc
	v_pk_fma_f32 v[110:111], v[112:113], s[88:89], v[128:129] op_sel_hi:[1,0,1] neg_lo:[0,0,1] neg_hi:[0,0,1]
	v_pk_mul_f32 v[112:113], v[114:115], s[88:89] op_sel_hi:[1,0]
	v_sub_f32_e32 v127, v127, v128
	v_exp_f32_e32 v130, v113
	v_exp_f32_e32 v131, v112
	v_cmp_lt_f32_e32 vcc, s5, v113
	v_sub_f32_e32 v127, v127, v129
	v_add_f32_e32 v130, 1.0, v130
	v_log_f32_e32 v130, v130
	v_add_f32_e32 v131, 1.0, v131
	v_log_f32_e32 v134, v131
	v_cndmask_b32_e32 v131, v130, v113, vcc
	v_cmp_lt_f32_e32 vcc, s5, v112
	s_nop 1
	v_cndmask_b32_e32 v130, v134, v112, vcc
	v_pk_fma_f32 v[112:113], v[114:115], s[88:89], v[130:131] op_sel_hi:[1,0,1] neg_lo:[0,0,1] neg_hi:[0,0,1]
	v_sub_f32_e32 v114, v127, v130
	v_sub_f32_e32 v127, v114, v131
	v_pk_add_f32 v[114:115], v[128:129], 0 neg_lo:[1,1] neg_hi:[1,1]
	v_pk_add_f32 v[128:129], v[130:131], 0 neg_lo:[1,1] neg_hi:[1,1]
	v_cvt_pk_bf16_f32 v114, v114, v115
	v_cvt_pk_bf16_f32 v115, v128, v129
	ds_write2_b64 v126, v[132:133], v[114:115] offset0:8 offset1:12
	v_pk_mul_f32 v[114:115], v[100:101], s[88:89] op_sel_hi:[1,0]
	v_pk_mul_f32 v[128:129], v[102:103], s[88:89] op_sel_hi:[1,0]
	v_exp_f32_e32 v130, v115
	v_exp_f32_e32 v131, v114
	v_cmp_lt_f32_e32 vcc, s5, v115
	v_exp_f32_e32 v132, v129
	v_add_f32_e32 v130, 1.0, v130
	v_log_f32_e32 v130, v130
	v_add_f32_e32 v131, 1.0, v131
	v_log_f32_e32 v133, v131
	v_cndmask_b32_e32 v131, v130, v115, vcc
	v_cmp_lt_f32_e32 vcc, s5, v114
	s_nop 1
	v_cndmask_b32_e32 v130, v133, v114, vcc
	v_exp_f32_e32 v133, v128
	v_pk_fma_f32 v[114:115], v[100:101], s[88:89], v[130:131] op_sel_hi:[1,0,1] neg_lo:[0,0,1] neg_hi:[0,0,1]
	v_add_f32_e32 v100, 1.0, v132
	v_log_f32_e32 v100, v100
	v_add_f32_e32 v101, 1.0, v133
	v_log_f32_e32 v101, v101
	v_cmp_lt_f32_e32 vcc, s5, v129
	s_nop 1
	v_cndmask_b32_e32 v129, v100, v129, vcc
	v_cmp_lt_f32_e32 vcc, s5, v128
	s_nop 1
	v_cndmask_b32_e32 v128, v101, v128, vcc
	v_pk_fma_f32 v[100:101], v[102:103], s[88:89], v[128:129] op_sel_hi:[1,0,1] neg_lo:[0,0,1] neg_hi:[0,0,1]
	v_pk_add_f32 v[102:103], v[130:131], 0 neg_lo:[1,1] neg_hi:[1,1]
	s_nop 0
	v_cvt_pk_bf16_f32 v132, v102, v103
	v_pk_add_f32 v[102:103], v[128:129], 0 neg_lo:[1,1] neg_hi:[1,1]
	s_nop 0
	v_cvt_pk_bf16_f32 v133, v102, v103
	v_sub_f32_e32 v102, v127, v130
	v_sub_f32_e32 v127, v102, v131
	v_pk_mul_f32 v[102:103], v[104:105], s[88:89] op_sel_hi:[1,0]
	v_sub_f32_e32 v127, v127, v128
	v_exp_f32_e32 v130, v103
	v_exp_f32_e32 v128, v102
	v_sub_f32_e32 v127, v127, v129
	v_cmp_lt_f32_e32 vcc, s5, v103
	v_add_f32_e32 v129, 1.0, v130
	v_log_f32_e32 v129, v129
	v_add_f32_e32 v128, 1.0, v128
	v_log_f32_e32 v128, v128
; #define LAS __attribute__((address_space(3)))
; __device__ __forceinline__ unsigned pk2(float lo, float hi) { return pg8::cvt_pk_bf16(lo, hi); }
; __device__ __forceinline__ f32x4 mfma16(bf16x8 a, bf16x8 b, f32x4 c) { return __builtin_amdgcn_mfma_f32_16x16x32_bf16(a, b, c, 0, 0, 0); }
; #define LDS_FENCE() asm volatile("s_waitcnt lgkmcnt(0)" ::: "memory")
; template <bool DIAG, int NST>
; __device__ __forceinline__ void attn_tile(LAS unsigned char* lds, const bf16x8 (&qf)[4], f32x4 (&accO)[8], float& R, int w, int l15, int quad, int tl, bf16x8 U1, bf16x8 T0, bf16x8 T1) {
;     ...
;     for (int st = 0; st < NST; ++st) {
;         u32x2 wv = {0u, 0u};
;         if (true) { float lk[4];
; #pragma unroll
;             for (int j = 0; j < 4; ++j) { const float z2 = z[st][j] * SCALE2; float sp = __builtin_amdgcn_logf(1.0f + __builtin_amdgcn_exp2f(z2)); sp = (z2 > 64.0f) ? z2 : sp;
;                 if (DIAG) { const int s = 16 * st + 4 * quad + j; lk[j] = (s < tl) ? -sp : 0.f; } else lk[j] = -sp;
;                 z[st][j] = z2 - sp; rs += lk[j]; }
;             wv.x = pk2(lk[0], lk[1]); wv.y = pk2(lk[2], lk[3]); }
;         *(LAS u32x2*)(lds + AT_P + tl * 272 + (16 * st + 4 * quad) * 2) = wv;
;         if (st & 1) __builtin_amdgcn_sched_barrier(0); }
;     LDS_FENCE();
;     { bf16x8 bb[4];
; #pragma unroll
;       for (int kj = 0; kj < NST / 2; ++kj) bb[kj] = *(const LAS bf16x8*)(lds + AT_P + tl * 272 + (32 * kj + 8 * quad) * 2);
;       rs += __shfl_xor(rs, 16); rs += __shfl_xor(rs, 32);
; #pragma unroll
;       for (int st = 0; st < NST; ++st) {
;           u32x2 wv = {0u, 0u};
;           if (true) {
;               f32x4 cs = (f32x4){0.f, 0.f, 0.f, 0.f};
; #pragma unroll
;               for (int kj = st >> 1; kj < NST / 2; ++kj) { const int dd = 2 * kj - st; cs = mfma16(dd == 0 ? T0 : (dd == -1 ? T1 : U1), bb[kj], cs); }
	v_cndmask_b32_e32 v129, v129, v103, vcc
	v_cmp_lt_f32_e32 vcc, s5, v102
	s_nop 1
	v_cndmask_b32_e32 v128, v128, v102, vcc
	v_pk_fma_f32 v[102:103], v[104:105], s[88:89], v[128:129] op_sel_hi:[1,0,1] neg_lo:[0,0,1] neg_hi:[0,0,1]
	v_pk_mul_f32 v[104:105], v[106:107], s[88:89] op_sel_hi:[1,0]
	v_sub_f32_e32 v127, v127, v128
	v_exp_f32_e32 v130, v105
	v_exp_f32_e32 v131, v104
	v_cmp_lt_f32_e32 vcc, s5, v105
	v_sub_f32_e32 v127, v127, v129
	v_add_f32_e32 v130, 1.0, v130
	v_log_f32_e32 v130, v130
	v_add_f32_e32 v131, 1.0, v131
	v_log_f32_e32 v134, v131
	v_cndmask_b32_e32 v131, v130, v105, vcc
	v_cmp_lt_f32_e32 vcc, s5, v104
	s_nop 1
	v_cndmask_b32_e32 v130, v134, v104, vcc
	v_pk_fma_f32 v[104:105], v[106:107], s[88:89], v[130:131] op_sel_hi:[1,0,1] neg_lo:[0,0,1] neg_hi:[0,0,1]
	v_sub_f32_e32 v106, v127, v130
	v_sub_f32_e32 v127, v106, v131
	v_pk_add_f32 v[106:107], v[128:129], 0 neg_lo:[1,1] neg_hi:[1,1]
	v_pk_add_f32 v[128:129], v[130:131], 0 neg_lo:[1,1] neg_hi:[1,1]
	v_cvt_pk_bf16_f32 v106, v106, v107
	v_cvt_pk_bf16_f32 v107, v128, v129
	ds_write2_b64 v126, v[132:133], v[106:107] offset0:16 offset1:20
	v_pk_mul_f32 v[106:107], v[96:97], s[88:89] op_sel_hi:[1,0]
	v_pk_mul_f32 v[128:129], v[98:99], s[88:89] op_sel_hi:[1,0]
	v_exp_f32_e32 v130, v107
	v_exp_f32_e32 v131, v106
	v_exp_f32_e32 v132, v129
	v_cmp_lt_f32_e32 vcc, s5, v107
	v_add_f32_e32 v130, 1.0, v130
	v_log_f32_e32 v130, v130
	v_add_f32_e32 v131, 1.0, v131
	v_log_f32_e32 v131, v131
	v_cndmask_b32_e32 v107, v130, v107, vcc
	v_exp_f32_e32 v130, v128
	v_cmp_lt_f32_e32 vcc, s5, v106
	v_add_f32_e32 v130, 1.0, v130
	s_nop 0
	v_cndmask_b32_e32 v106, v131, v106, vcc
	v_add_f32_e32 v131, 1.0, v132
	v_log_f32_e32 v131, v131
	v_log_f32_e32 v130, v130
	v_cmp_lt_f32_e32 vcc, s5, v129
	v_pk_fma_f32 v[96:97], v[96:97], s[88:89], v[106:107] op_sel_hi:[1,0,1] neg_lo:[0,0,1] neg_hi:[0,0,1]
	s_nop 0
	v_cndmask_b32_e32 v129, v131, v129, vcc
	v_cmp_lt_f32_e32 vcc, s5, v128
	s_nop 1
	v_cndmask_b32_e32 v128, v130, v128, vcc
	v_pk_add_f32 v[130:131], v[106:107], 0 neg_lo:[1,1] neg_hi:[1,1]
	v_sub_f32_e32 v106, v127, v106
	v_pk_add_f32 v[132:133], v[128:129], 0 neg_lo:[1,1] neg_hi:[1,1]
	v_sub_f32_e32 v127, v106, v107
	v_pk_mul_f32 v[106:107], v[92:93], s[88:89] op_sel_hi:[1,0]
	v_cvt_pk_bf16_f32 v130, v130, v131
	v_cvt_pk_bf16_f32 v131, v132, v133
	v_exp_f32_e32 v132, v107
	v_pk_fma_f32 v[98:99], v[98:99], s[88:89], v[128:129] op_sel_hi:[1,0,1] neg_lo:[0,0,1] neg_hi:[0,0,1]
	v_sub_f32_e32 v127, v127, v128
	v_exp_f32_e32 v128, v106
	v_sub_f32_e32 v127, v127, v129
	v_add_f32_e32 v129, 1.0, v132
	v_log_f32_e32 v129, v129
	v_add_f32_e32 v128, 1.0, v128
	v_log_f32_e32 v128, v128
	v_cmp_lt_f32_e32 vcc, s5, v107
	s_nop 1
	v_cndmask_b32_e32 v153, v129, v107, vcc
	v_cmp_lt_f32_e32 vcc, s5, v106
	s_nop 1
	v_cndmask_b32_e32 v152, v128, v106, vcc
	v_pk_mul_f32 v[106:107], v[94:95], s[88:89] op_sel_hi:[1,0]
	v_sub_f32_e32 v127, v127, v152
	v_exp_f32_e32 v128, v107
	v_exp_f32_e32 v129, v106
	v_cmp_lt_f32_e32 vcc, s5, v107
	v_sub_f32_e32 v127, v127, v153
	v_add_f32_e32 v128, 1.0, v128
	v_log_f32_e32 v128, v128
	v_add_f32_e32 v129, 1.0, v129
	v_log_f32_e32 v129, v129
	v_cndmask_b32_e32 v155, v128, v107, vcc
	v_cmp_lt_f32_e32 vcc, s5, v106
	s_nop 1
	v_cndmask_b32_e32 v154, v129, v106, vcc
	v_sub_f32_e32 v106, v127, v154
	v_sub_f32_e32 v127, v106, v155
	v_pk_add_f32 v[106:107], v[152:153], 0 neg_lo:[1,1] neg_hi:[1,1]
	v_pk_add_f32 v[128:129], v[154:155], 0 neg_lo:[1,1] neg_hi:[1,1]
	v_cvt_pk_bf16_f32 v106, v106, v107
	v_cvt_pk_bf16_f32 v107, v128, v129
	ds_write2_b64 v126, v[130:131], v[106:107] offset0:24 offset1:28
	s_waitcnt lgkmcnt(0)
	ds_read_b128 v[128:131], v167
	ds_read_b128 v[132:135], v167 offset:64
	s_mov_b32 s78, s76
	s_mov_b32 s79, s76
	s_mov_b32 s77, s76
	v_mov_b64_e32 v[142:143], s[78:79]
	v_mov_b64_e32 v[140:141], s[76:77]
	s_waitcnt lgkmcnt(1)
	v_mfma_f32_16x16x32_bf16 v[136:139], v[4:7], v[128:131], 0
	ds_read_b128 v[144:147], v167 offset:128
	ds_read_b128 v[148:151], v167 offset:192
	v_and_b32_e32 v107, 64, v206
	v_xor_b32_e32 v106, 16, v206
	s_waitcnt lgkmcnt(2)
	v_mfma_f32_16x16x32_bf16 v[136:139], v[140:143], v[132:135], v[136:139]
	v_add_u32_e32 v214, 64, v107
	v_cmp_lt_i32_e32 vcc, v106, v214
	v_pk_fma_f32 v[94:95], v[94:95], s[88:89], v[154:155] op_sel_hi:[1,0,1] neg_lo:[0,0,1] neg_hi:[0,0,1]
	s_waitcnt lgkmcnt(1)
	v_mfma_f32_16x16x32_bf16 v[136:139], v[140:143], v[144:147], v[136:139]
	v_cndmask_b32_e32 v106, v206, v106, vcc
	v_lshlrev_b32_e32 v106, 2, v106
	ds_bpermute_b32 v215, v106, v127
	v_mfma_f32_16x16x32_bf16 v[128:131], v[0:3], v[128:131], 0
	v_fma_f32 v92, v92, s88, -v152
	v_fma_f32 v93, v93, s88, -v153
	s_waitcnt lgkmcnt(1)
; #define LAS __attribute__((address_space(3)))
; __device__ __forceinline__ unsigned pk2(float lo, float hi) { return pg8::cvt_pk_bf16(lo, hi); }
; __device__ __forceinline__ f32x4 mfma16(bf16x8 a, bf16x8 b, f32x4 c) { return __builtin_amdgcn_mfma_f32_16x16x32_bf16(a, b, c, 0, 0, 0); }
; #define LDS_FENCE() asm volatile("s_waitcnt lgkmcnt(0)" ::: "memory")
; template <bool DIAG, int NST>
; __device__ __forceinline__ void attn_tile(LAS unsigned char* lds, const bf16x8 (&qf)[4], f32x4 (&accO)[8], float& R, int w, int l15, int quad, int tl, bf16x8 U1, bf16x8 T0, bf16x8 T1) {
;     ...
;     { bf16x8 bb[4];
; #pragma unroll
;       for (int kj = 0; kj < NST / 2; ++kj) bb[kj] = *(const LAS bf16x8*)(lds + AT_P + tl * 272 + (32 * kj + 8 * quad) * 2);
;       rs += __shfl_xor(rs, 16); rs += __shfl_xor(rs, 32);
; #pragma unroll
;       for (int st = 0; st < NST; ++st) {
;           u32x2 wv = {0u, 0u};
;           if (true) {
;               f32x4 cs = (f32x4){0.f, 0.f, 0.f, 0.f};
; #pragma unroll
;               for (int kj = st >> 1; kj < NST / 2; ++kj) { const int dd = 2 * kj - st; cs = mfma16(dd == 0 ? T0 : (dd == -1 ? T1 : U1), bb[kj], cs); }
;               float a[4];
; #pragma unroll
;               for (int j = 0; j < 4; ++j) { float av = __builtin_amdgcn_exp2f(z[st][j] + cs[j] + R);
;                   if (DIAG) { const int s = 16 * st + 4 * quad + j; av = (s < tl) ? av : 0.f; }
;                   a[j] = av; }
;               wv.x = pk2(a[0], a[1]); wv.y = pk2(a[2], a[3]); }
;           *(LAS u32x2*)(lds + AT_P + tl * 272 + (16 * st + 4 * quad) * 2) = wv; } }
;     R += rs;
;     LDS_FENCE();
	v_mfma_f32_16x16x32_bf16 v[136:139], v[140:143], v[148:151], v[136:139]
	v_mfma_f32_16x16x32_bf16 v[128:131], v[140:143], v[132:135], v[128:131]
	s_nop 6
	v_add_f32_e32 v106, v120, v136
	v_add_f32_e32 v120, v122, v138
	v_add_f32_e32 v120, v165, v120
	v_add_f32_e32 v107, v121, v137
	v_exp_f32_e32 v136, v120
	v_add_f32_e32 v137, v123, v139
	v_mfma_f32_16x16x32_bf16 v[120:123], v[140:143], v[144:147], v[128:131]
	v_add_f32_e32 v106, v165, v106
	v_add_f32_e32 v107, v165, v107
	v_exp_f32_e32 v106, v106
	v_exp_f32_e32 v107, v107
	v_mfma_f32_16x16x32_bf16 v[120:123], v[140:143], v[148:151], v[120:123]
	v_add_f32_e32 v128, v165, v137
	v_exp_f32_e32 v128, v128
	v_cvt_pk_bf16_f32 v106, v106, v107
	s_nop 4
	v_add_f32_e32 v107, v116, v120
	v_add_f32_e32 v107, v165, v107
	v_exp_f32_e32 v120, v107
	v_add_f32_e32 v107, v117, v121
	v_add_f32_e32 v107, v165, v107
	v_exp_f32_e32 v121, v107
	v_add_f32_e32 v107, v118, v122
	v_add_f32_e32 v107, v165, v107
	v_exp_f32_e32 v122, v107
	v_add_f32_e32 v107, v119, v123
	v_mfma_f32_16x16x32_bf16 v[116:119], v[4:7], v[132:135], 0
	v_add_f32_e32 v107, v165, v107
	v_exp_f32_e32 v123, v107
	v_cvt_pk_bf16_f32 v107, v136, v128
	v_mfma_f32_16x16x32_bf16 v[116:119], v[140:143], v[144:147], v[116:119]
	v_cvt_pk_bf16_f32 v120, v120, v121
	v_cvt_pk_bf16_f32 v121, v122, v123
	ds_write2_b64 v126, v[106:107], v[120:121] offset1:4
	v_mfma_f32_16x16x32_bf16 v[116:119], v[140:143], v[148:151], v[116:119]
	v_mfma_f32_16x16x32_bf16 v[120:123], v[0:3], v[132:135], 0
	s_nop 6
	v_add_f32_e32 v106, v124, v116
	v_add_f32_e32 v106, v165, v106
	v_exp_f32_e32 v116, v106
	v_add_f32_e32 v106, v125, v117
	v_add_f32_e32 v106, v165, v106
	v_exp_f32_e32 v117, v106
	v_add_f32_e32 v106, v108, v118
	v_add_f32_e32 v106, v165, v106
	v_exp_f32_e32 v118, v106
	v_add_f32_e32 v119, v109, v119
	v_mfma_f32_16x16x32_bf16 v[106:109], v[140:143], v[144:147], v[120:123]
	v_add_f32_e32 v119, v165, v119
	v_exp_f32_e32 v119, v119
	v_cvt_pk_bf16_f32 v116, v116, v117
	v_mfma_f32_16x16x32_bf16 v[106:109], v[140:143], v[148:151], v[106:109]
	v_cvt_pk_bf16_f32 v117, v118, v119
	s_nop 6
	v_add_f32_e32 v106, v110, v106
	v_add_f32_e32 v106, v165, v106
	v_exp_f32_e32 v110, v106
	v_add_f32_e32 v106, v111, v107
	v_add_f32_e32 v106, v165, v106
	v_exp_f32_e32 v111, v106
	v_add_f32_e32 v106, v112, v108
	v_add_f32_e32 v106, v165, v106
	v_exp_f32_e32 v112, v106
	v_add_f32_e32 v106, v113, v109
	v_add_f32_e32 v106, v165, v106
	v_exp_f32_e32 v113, v106
	v_mfma_f32_16x16x32_bf16 v[106:109], v[4:7], v[144:147], 0
	v_cvt_pk_bf16_f32 v110, v110, v111
	v_cvt_pk_bf16_f32 v111, v112, v113
	v_mfma_f32_16x16x32_bf16 v[106:109], v[140:143], v[148:151], v[106:109]
	ds_write2_b64 v126, v[116:117], v[110:111] offset0:8 offset1:12
	v_mfma_f32_16x16x32_bf16 v[110:113], v[0:3], v[144:147], 0
	s_nop 5
	v_add_f32_e32 v106, v114, v106
	v_add_f32_e32 v106, v165, v106
	v_exp_f32_e32 v114, v106
	v_add_f32_e32 v106, v115, v107
	v_add_f32_e32 v100, v100, v108
	v_add_f32_e32 v106, v165, v106
	v_add_f32_e32 v100, v165, v100
	v_exp_f32_e32 v115, v106
	v_exp_f32_e32 v116, v100
	v_add_f32_e32 v100, v101, v109
	v_mfma_f32_16x16x32_bf16 v[106:109], v[140:143], v[148:151], v[110:113]
	v_add_f32_e32 v100, v165, v100
	v_exp_f32_e32 v101, v100
	s_nop 0
	v_cvt_pk_bf16_f32 v101, v116, v101
	s_nop 3
	v_add_f32_e32 v100, v102, v106
	v_add_f32_e32 v100, v165, v100
	v_exp_f32_e32 v102, v100
	v_add_f32_e32 v100, v103, v107
	v_add_f32_e32 v100, v165, v100
	v_exp_f32_e32 v103, v100
	v_add_f32_e32 v100, v104, v108
	v_add_f32_e32 v100, v165, v100
	v_exp_f32_e32 v104, v100
	v_add_f32_e32 v100, v105, v109
	v_add_f32_e32 v100, v165, v100
	v_exp_f32_e32 v105, v100
	v_cvt_pk_bf16_f32 v100, v114, v115
	v_cvt_pk_bf16_f32 v102, v102, v103
	v_cvt_pk_bf16_f32 v103, v104, v105
	ds_write2_b64 v126, v[100:101], v[102:103] offset0:16 offset1:20
	v_mfma_f32_16x16x32_bf16 v[100:103], v[4:7], v[148:151], 0
	s_waitcnt lgkmcnt(3)
	v_add_f32_e32 v104, v127, v215
	s_nop 5
	v_add_f32_e32 v96, v96, v100
	v_add_f32_e32 v97, v97, v101
	v_add_f32_e32 v96, v165, v96
	v_add_f32_e32 v97, v165, v97
	v_exp_f32_e32 v96, v96
	v_exp_f32_e32 v97, v97
	v_add_f32_e32 v98, v98, v102
	v_add_f32_e32 v98, v165, v98
	v_exp_f32_e32 v101, v98
	v_add_f32_e32 v98, v99, v103
	v_add_f32_e32 v98, v165, v98
	v_exp_f32_e32 v102, v98
	v_cvt_pk_bf16_f32 v100, v96, v97
	v_mfma_f32_16x16x32_bf16 v[96:99], v[0:3], v[148:151], 0
	v_xor_b32_e32 v103, 32, v206
	v_cmp_lt_i32_e32 vcc, v103, v214
	v_cvt_pk_bf16_f32 v101, v101, v102
	s_nop 0
	v_cndmask_b32_e32 v103, v206, v103, vcc
	s_nop 2
	v_add_f32_e32 v92, v92, v96
	v_add_f32_e32 v93, v93, v97
	v_add_f32_e32 v94, v94, v98
	v_add_f32_e32 v95, v95, v99
	v_add_f32_e32 v92, v165, v92
	v_add_f32_e32 v93, v165, v93
	v_add_f32_e32 v94, v165, v94
	v_add_f32_e32 v95, v165, v95
	v_exp_f32_e32 v92, v92
	v_exp_f32_e32 v93, v93
	v_exp_f32_e32 v94, v94
	v_exp_f32_e32 v95, v95
	v_lshlrev_b32_e32 v103, 2, v103
	ds_bpermute_b32 v96, v103, v104
	v_cvt_pk_bf16_f32 v92, v92, v93
	v_cvt_pk_bf16_f32 v93, v94, v95
	ds_write2_b64 v126, v[100:101], v[92:93] offset0:24 offset1:28
	s_waitcnt lgkmcnt(0)
	s_waitcnt lgkmcnt(1)
	v_add_f32_e32 v214, v104, v96
	s_cbranch_execz .LBB0_987
	s_branch .LBB0_1001
; #define LAS __attribute__((address_space(3)))
; __device__ __forceinline__ unsigned pk2(float lo, float hi) { return pg8::cvt_pk_bf16(lo, hi); }
; __device__ __forceinline__ f32x4 mfma16(bf16x8 a, bf16x8 b, f32x4 c) { return __builtin_amdgcn_mfma_f32_16x16x32_bf16(a, b, c, 0, 0, 0); }
; template <bool DIAG, int NST>
; __device__ __forceinline__ void attn_tile(LAS unsigned char* lds, const bf16x8 (&qf)[4], f32x4 (&accO)[8], float& R, int w, int l15, int quad, int tl, bf16x8 U1, bf16x8 T0, bf16x8 T1) {
;     ...
;     f32x4 z[8];
; #pragma unroll
;     for (int st = 0; st < NST; ++st) { z[st] = (f32x4){0.f, 0.f, 0.f, 0.f};
;         if (true) {
; #pragma unroll
;             for (int ks = 0; ks < 4; ++ks) { const bf16x8 a = *(const LAS bf16x8*)(lds + AT_KS + (16 * st + l15) * 272 + (32 * ks + 8 * quad) * 2); z[st] = mfma16(a, qf[ks], z[st]); } }
;         if (st & 1) __builtin_amdgcn_sched_barrier(0); }
;     float rs = 0.f;
; #pragma unroll
;     for (int st = 0; st < NST; ++st) {
;         u32x2 wv = {0u, 0u};
;         if (true) { float lk[4];
; #pragma unroll
;             for (int j = 0; j < 4; ++j) { const float z2 = z[st][j] * SCALE2; float sp = __builtin_amdgcn_logf(1.0f + __builtin_amdgcn_exp2f(z2)); sp = (z2 > 64.0f) ? z2 : sp;
;                 if (DIAG) { const int s = 16 * st + 4 * quad + j; lk[j] = (s < tl) ? -sp : 0.f; } else lk[j] = -sp;
;                 z[st][j] = z2 - sp; rs += lk[j]; }
;             wv.x = pk2(lk[0], lk[1]); wv.y = pk2(lk[2], lk[3]); }
;         *(LAS u32x2*)(lds + AT_P + tl * 272 + (16 * st + 4 * quad) * 2) = wv;
.LBB0_986:
.LBB0_987:
	s_mov_b64 s[78:79], -1
	s_and_b64 vcc, exec, s[86:87]
	s_cbranch_vccz .LBB0_999
	ds_read_b128 v[92:95], v173 offset:64
	ds_read_b128 v[96:99], v173 offset:128
	ds_read_b128 v[100:103], v173 offset:192
	ds_read_b128 v[104:107], v173 offset:4352
	ds_read_b128 v[108:111], v173 offset:4416
	ds_read_b128 v[112:115], v173 offset:4480
	ds_read_b128 v[116:119], v173 offset:4544
	s_mov_b64 s[94:95], -1
	s_mov_b64 s[92:93], 0
	s_cmp_lt_i32 s81, 2
	s_mov_b64 s[78:79], 0
	s_cbranch_scc1 .LBB0_994
	s_cmp_eq_u32 s81, 2
	s_mov_b64 s[78:79], -1
	s_cbranch_scc0 .LBB0_991
	s_waitcnt lgkmcnt(7)
	v_mfma_f32_16x16x32_bf16 v[120:123], v[88:91], v[24:27], 0
	s_waitcnt lgkmcnt(6)
	v_mfma_f32_16x16x32_bf16 v[120:123], v[92:95], v[28:31], v[120:123]
	s_waitcnt lgkmcnt(5)
	v_mfma_f32_16x16x32_bf16 v[120:123], v[96:99], v[32:35], v[120:123]
	s_waitcnt lgkmcnt(4)
	v_mfma_f32_16x16x32_bf16 v[140:143], v[100:103], v[36:39], v[120:123]
	s_waitcnt lgkmcnt(3)
	v_mfma_f32_16x16x32_bf16 v[120:123], v[104:107], v[24:27], 0
	s_waitcnt lgkmcnt(2)
	v_mfma_f32_16x16x32_bf16 v[120:123], v[108:111], v[28:31], v[120:123]
	s_waitcnt lgkmcnt(1)
	v_mfma_f32_16x16x32_bf16 v[120:123], v[112:115], v[32:35], v[120:123]
	s_waitcnt lgkmcnt(0)
	v_mfma_f32_16x16x32_bf16 v[136:139], v[116:119], v[36:39], v[120:123]
	s_nop 5
	ds_read_b128 v[120:123], v173 offset:8704
	ds_read_b128 v[124:127], v173 offset:8768
	s_waitcnt lgkmcnt(1)
	v_mfma_f32_16x16x32_bf16 v[120:123], v[120:123], v[24:27], 0
	s_waitcnt lgkmcnt(0)
	v_mfma_f32_16x16x32_bf16 v[120:123], v[124:127], v[28:31], v[120:123]
	ds_read_b128 v[124:127], v173 offset:8832
	s_waitcnt lgkmcnt(0)
	v_mfma_f32_16x16x32_bf16 v[120:123], v[124:127], v[32:35], v[120:123]
	ds_read_b128 v[124:127], v173 offset:8896
	s_waitcnt lgkmcnt(0)
	v_mfma_f32_16x16x32_bf16 v[132:135], v[124:127], v[36:39], v[120:123]
	s_nop 4
	ds_read_b128 v[120:123], v173 offset:13056
	ds_read_b128 v[124:127], v173 offset:13120
	s_waitcnt lgkmcnt(1)
	v_mfma_f32_16x16x32_bf16 v[120:123], v[120:123], v[24:27], 0
	s_waitcnt lgkmcnt(0)
	v_mfma_f32_16x16x32_bf16 v[120:123], v[124:127], v[28:31], v[120:123]
	ds_read_b128 v[124:127], v173 offset:13184
	s_waitcnt lgkmcnt(0)
	v_mfma_f32_16x16x32_bf16 v[120:123], v[124:127], v[32:35], v[120:123]
	ds_read_b128 v[124:127], v173 offset:13248
	s_waitcnt lgkmcnt(0)
	v_mfma_f32_16x16x32_bf16 v[128:131], v[124:127], v[36:39], v[120:123]
	s_nop 4
	ds_read_b128 v[120:123], v173 offset:17408
	ds_read_b128 v[124:127], v173 offset:17472
	s_waitcnt lgkmcnt(1)
	v_mfma_f32_16x16x32_bf16 v[120:123], v[120:123], v[24:27], 0
	ds_read_b128 v[144:147], v173 offset:21824
	s_waitcnt lgkmcnt(1)
	v_mfma_f32_16x16x32_bf16 v[120:123], v[124:127], v[28:31], v[120:123]
	ds_read_b128 v[124:127], v173 offset:17536
	s_waitcnt lgkmcnt(0)
	v_mfma_f32_16x16x32_bf16 v[120:123], v[124:127], v[32:35], v[120:123]
	ds_read_b128 v[124:127], v173 offset:17600
	s_waitcnt lgkmcnt(0)
	v_mfma_f32_16x16x32_bf16 v[124:127], v[124:127], v[36:39], v[120:123]
	s_nop 4
	ds_read_b128 v[120:123], v173 offset:21760
	s_waitcnt lgkmcnt(0)
	v_mfma_f32_16x16x32_bf16 v[120:123], v[120:123], v[24:27], 0
	v_mfma_f32_16x16x32_bf16 v[120:123], v[144:147], v[28:31], v[120:123]
	ds_read_b128 v[144:147], v173 offset:21888
	s_waitcnt lgkmcnt(0)
	v_mfma_f32_16x16x32_bf16 v[120:123], v[144:147], v[32:35], v[120:123]
	ds_read_b128 v[144:147], v173 offset:21952
	s_waitcnt lgkmcnt(0)
	v_mfma_f32_16x16x32_bf16 v[120:123], v[144:147], v[36:39], v[120:123]
	v_mul_f32_e32 v144, 0x3e0293ee, v140
	v_exp_f32_e32 v145, v144
	v_cmp_lt_f32_e32 vcc, s5, v144
	v_add_f32_e32 v145, 1.0, v145
	v_log_f32_e32 v145, v145
	s_nop 0
	v_cndmask_b32_e32 v144, v145, v144, vcc
	v_cndmask_b32_e64 v145, 0, -v144, s[8:9]
	v_fma_f32 v144, v140, s88, -v144
	v_mul_f32_e32 v140, 0x3e0293ee, v141
	v_exp_f32_e32 v146, v140
	v_cmp_lt_f32_e32 vcc, s5, v140
	v_add_f32_e32 v146, 1.0, v146
	v_log_f32_e32 v146, v146
	s_nop 0
	v_cndmask_b32_e32 v140, v146, v140, vcc
	v_cndmask_b32_e64 v148, 0, -v140, s[10:11]
	v_fma_f32 v141, v141, s88, -v140
	v_mul_f32_e32 v140, 0x3e0293ee, v142
	v_exp_f32_e32 v146, v140
	v_cmp_lt_f32_e32 vcc, s5, v140
	v_add_f32_e32 v146, 1.0, v146
	v_log_f32_e32 v146, v146
	s_nop 0
	v_cndmask_b32_e32 v140, v146, v140, vcc
	v_cndmask_b32_e64 v149, 0, -v140, s[12:13]
	v_fma_f32 v142, v142, s88, -v140
	v_mul_f32_e32 v140, 0x3e0293ee, v143
	v_exp_f32_e32 v146, v140
	v_cmp_lt_f32_e32 vcc, s5, v140
	v_add_f32_e32 v146, 1.0, v146
	v_log_f32_e32 v146, v146
	s_nop 0
	v_cndmask_b32_e32 v140, v146, v140, vcc
	v_cvt_pk_bf16_f32 v146, v145, v148
	v_add_f32_e32 v145, 0, v145
	v_cndmask_b32_e64 v150, 0, -v140, s[14:15]
	v_add_f32_e32 v145, v148, v145
	v_mul_f32_e32 v148, 0x3e0293ee, v136
	v_cvt_pk_bf16_f32 v147, v149, v150
	v_add_f32_e32 v145, v149, v145
	v_exp_f32_e32 v149, v148
	v_cmp_lt_f32_e32 vcc, s5, v148
	v_add_f32_e32 v145, v150, v145
	v_fma_f32 v143, v143, s88, -v140
	v_add_f32_e32 v149, 1.0, v149
	v_log_f32_e32 v149, v149
	v_add_u32_e32 v140, v174, v158
	v_cndmask_b32_e32 v148, v149, v148, vcc
	v_cndmask_b32_e64 v149, 0, -v148, s[16:17]
	v_fma_f32 v136, v136, s88, -v148
	v_mul_f32_e32 v148, 0x3e0293ee, v137
	v_exp_f32_e32 v150, v148
	v_cmp_lt_f32_e32 vcc, s5, v148
	v_add_f32_e32 v145, v145, v149
	v_add_f32_e32 v150, 1.0, v150
	v_log_f32_e32 v150, v150
	s_nop 0
	v_cndmask_b32_e32 v148, v150, v148, vcc
	v_cndmask_b32_e64 v150, 0, -v148, s[18:19]
	v_fma_f32 v137, v137, s88, -v148
	v_mul_f32_e32 v148, 0x3e0293ee, v138
	v_exp_f32_e32 v151, v148
	v_cmp_lt_f32_e32 vcc, s5, v148
	v_add_f32_e32 v145, v150, v145
	v_add_f32_e32 v151, 1.0, v151
	v_log_f32_e32 v151, v151
	s_nop 0
	v_cndmask_b32_e32 v148, v151, v148, vcc
; #define LAS __attribute__((address_space(3)))
; __device__ __forceinline__ unsigned pk2(float lo, float hi) { return pg8::cvt_pk_bf16(lo, hi); }
; template <bool DIAG, int NST>
; __device__ __forceinline__ void attn_tile(LAS unsigned char* lds, const bf16x8 (&qf)[4], f32x4 (&accO)[8], float& R, int w, int l15, int quad, int tl, bf16x8 U1, bf16x8 T0, bf16x8 T1) {
;     ...
;     for (int st = 0; st < NST; ++st) {
;         u32x2 wv = {0u, 0u};
;         if (true) { float lk[4];
; #pragma unroll
;             for (int j = 0; j < 4; ++j) { const float z2 = z[st][j] * SCALE2; float sp = __builtin_amdgcn_logf(1.0f + __builtin_amdgcn_exp2f(z2)); sp = (z2 > 64.0f) ? z2 : sp;
;                 if (DIAG) { const int s = 16 * st + 4 * quad + j; lk[j] = (s < tl) ? -sp : 0.f; } else lk[j] = -sp;
;                 z[st][j] = z2 - sp; rs += lk[j]; }
;             wv.x = pk2(lk[0], lk[1]); wv.y = pk2(lk[2], lk[3]); }
;         *(LAS u32x2*)(lds + AT_P + tl * 272 + (16 * st + 4 * quad) * 2) = wv;
;         if (st & 1) __builtin_amdgcn_sched_barrier(0); }
	v_cndmask_b32_e64 v151, 0, -v148, s[20:21]
	v_fma_f32 v138, v138, s88, -v148
	v_mul_f32_e32 v148, 0x3e0293ee, v139
	v_exp_f32_e32 v152, v148
	v_cmp_lt_f32_e32 vcc, s5, v148
	v_add_f32_e32 v145, v151, v145
	v_add_f32_e32 v152, 1.0, v152
	v_log_f32_e32 v152, v152
	s_nop 0
	v_cndmask_b32_e32 v148, v152, v148, vcc
	v_cndmask_b32_e64 v152, 0, -v148, s[22:23]
	v_fma_f32 v139, v139, s88, -v148
	v_cvt_pk_bf16_f32 v148, v149, v150
	v_cvt_pk_bf16_f32 v149, v151, v152
	v_add_f32_e32 v145, v152, v145
	ds_write2_b64 v140, v[146:147], v[148:149] offset1:4
	v_mul_f32_e32 v146, 0x3e0293ee, v132
	v_exp_f32_e32 v147, v146
	v_cmp_lt_f32_e32 vcc, s5, v146
	v_add_f32_e32 v147, 1.0, v147
	v_log_f32_e32 v147, v147
	s_nop 0
	v_cndmask_b32_e32 v146, v147, v146, vcc
	v_cndmask_b32_e64 v147, 0, -v146, s[24:25]
	v_fma_f32 v132, v132, s88, -v146
	v_mul_f32_e32 v146, 0x3e0293ee, v133
	v_exp_f32_e32 v148, v146
	v_cmp_lt_f32_e32 vcc, s5, v146
	v_add_f32_e32 v148, 1.0, v148
	v_log_f32_e32 v148, v148
	s_nop 0
	v_cndmask_b32_e32 v146, v148, v146, vcc
	v_fma_f32 v154, v133, s88, -v146
	v_mul_f32_e32 v133, 0x3e0293ee, v134
	v_cndmask_b32_e64 v148, 0, -v146, s[26:27]
	v_exp_f32_e32 v146, v133
	v_cmp_lt_f32_e32 vcc, s5, v133
	v_add_f32_e32 v146, 1.0, v146
	v_log_f32_e32 v146, v146
	s_nop 0
	v_cndmask_b32_e32 v133, v146, v133, vcc
	v_cndmask_b32_e64 v146, 0, -v133, s[28:29]
	v_fma_f32 v155, v134, s88, -v133
	v_mul_f32_e32 v133, 0x3e0293ee, v135
	v_exp_f32_e32 v134, v133
	v_cmp_lt_f32_e32 vcc, s5, v133
	v_add_f32_e32 v134, 1.0, v134
	v_log_f32_e32 v134, v134
	s_nop 0
	v_cndmask_b32_e32 v133, v134, v133, vcc
	v_cndmask_b32_e64 v149, 0, -v133, s[30:31]
	v_fma_f32 v218, v135, s88, -v133
	v_add_f32_e32 v133, v145, v147
	v_add_f32_e32 v133, v148, v133
	v_mul_f32_e32 v145, 0x3e0293ee, v128
	v_cvt_pk_bf16_f32 v135, v146, v149
	v_add_f32_e32 v133, v146, v133
	v_exp_f32_e32 v146, v145
	v_cmp_lt_f32_e32 vcc, s5, v145
	v_add_f32_e32 v133, v149, v133
	v_cvt_pk_bf16_f32 v134, v147, v148
	v_add_f32_e32 v146, 1.0, v146
	v_log_f32_e32 v146, v146
	s_nop 0
	v_cndmask_b32_e32 v145, v146, v145, vcc
	v_cndmask_b32_e64 v146, 0, -v145, s[34:35]
	v_fma_f32 v145, v128, s88, -v145
	v_add_f32_e32 v128, v133, v146
	v_mul_f32_e32 v133, 0x3e0293ee, v129
	v_exp_f32_e32 v147, v133
	v_cmp_lt_f32_e32 vcc, s5, v133
	v_add_f32_e32 v147, 1.0, v147
	v_log_f32_e32 v147, v147
	s_nop 0
	v_cndmask_b32_e32 v133, v147, v133, vcc
	v_fma_f32 v219, v129, s88, -v133
	v_mul_f32_e32 v129, 0x3e0293ee, v130
	v_cndmask_b32_e64 v147, 0, -v133, s[36:37]
	v_exp_f32_e32 v133, v129
	v_cmp_lt_f32_e32 vcc, s5, v129
	v_add_f32_e32 v128, v147, v128
	v_add_f32_e32 v133, 1.0, v133
	v_log_f32_e32 v133, v133
	s_nop 0
	v_cndmask_b32_e32 v129, v133, v129, vcc
	v_cndmask_b32_e64 v133, 0, -v129, s[38:39]
	v_fma_f32 v220, v130, s88, -v129
	v_mul_f32_e32 v129, 0x3e0293ee, v131
	v_exp_f32_e32 v130, v129
	v_cmp_lt_f32_e32 vcc, s5, v129
	v_add_f32_e32 v128, v133, v128
	v_add_f32_e32 v130, 1.0, v130
	v_log_f32_e32 v130, v130
	s_nop 0
	v_cndmask_b32_e32 v129, v130, v129, vcc
	v_cndmask_b32_e64 v130, 0, -v129, s[40:41]
	v_fma_f32 v221, v131, s88, -v129
	v_add_f32_e32 v131, v130, v128
	v_cvt_pk_bf16_f32 v128, v146, v147
	v_cvt_pk_bf16_f32 v129, v133, v130
	ds_write2_b64 v140, v[134:135], v[128:129] offset0:8 offset1:12
	v_mul_f32_e32 v128, 0x3e0293ee, v124
	v_exp_f32_e32 v129, v128
	v_mul_f32_e32 v130, 0x3e0293ee, v125
	v_exp_f32_e32 v133, v130
	v_cmp_lt_f32_e32 vcc, s5, v128
	v_add_f32_e32 v129, 1.0, v129
	v_log_f32_e32 v129, v129
	v_add_f32_e32 v133, 1.0, v133
	v_log_f32_e32 v133, v133
	v_mul_f32_e32 v134, 0x3e0293ee, v127
	v_cndmask_b32_e32 v128, v129, v128, vcc
	v_fma_f32 v222, v124, s88, -v128
	v_mul_f32_e32 v124, 0x3e0293ee, v126
	v_cndmask_b32_e64 v129, 0, -v128, s[42:43]
	v_exp_f32_e32 v128, v124
	v_exp_f32_e32 v135, v134
	v_cmp_lt_f32_e32 vcc, s5, v130
	v_add_f32_e32 v128, 1.0, v128
	s_nop 0
	v_cndmask_b32_e32 v130, v133, v130, vcc
	v_log_f32_e32 v128, v128
	v_fma_f32 v223, v125, s88, -v130
	v_add_f32_e32 v125, 1.0, v135
	v_log_f32_e32 v125, v125
	v_cmp_lt_f32_e32 vcc, s5, v124
	v_cndmask_b32_e64 v133, 0, -v130, s[44:45]
	s_nop 0
	v_cndmask_b32_e32 v124, v128, v124, vcc
	v_cmp_lt_f32_e32 vcc, s5, v134
	v_cndmask_b32_e64 v128, 0, -v124, s[46:47]
	v_fma_f32 v226, v126, s88, -v124
	v_cndmask_b32_e32 v124, v125, v134, vcc
	v_cndmask_b32_e64 v126, 0, -v124, s[48:49]
	v_fma_f32 v227, v127, s88, -v124
	v_cvt_pk_bf16_f32 v124, v129, v133
	v_add_f32_e32 v127, v131, v129
	v_mul_f32_e32 v129, 0x3e0293ee, v120
	v_exp_f32_e32 v130, v129
	v_add_f32_e32 v127, v133, v127
	v_add_f32_e32 v127, v128, v127
	v_cvt_pk_bf16_f32 v125, v128, v126
	v_add_f32_e32 v126, v126, v127
	v_add_f32_e32 v127, 1.0, v130
	v_mul_f32_e32 v128, 0x3e0293ee, v121
	v_log_f32_e32 v127, v127
	v_exp_f32_e32 v130, v128
	v_cmp_lt_f32_e32 vcc, s5, v129
	s_nop 1
	v_cndmask_b32_e32 v228, v127, v129, vcc
	v_add_f32_e32 v129, 1.0, v130
	v_mul_f32_e32 v130, 0x3e0293ee, v122
	v_log_f32_e32 v129, v129
	v_exp_f32_e32 v131, v130
	v_cmp_lt_f32_e32 vcc, s5, v128
	v_cndmask_b32_e64 v127, 0, -v228, s[50:51]
	v_add_f32_e32 v126, v126, v127
	v_cndmask_b32_e32 v229, v129, v128, vcc
	v_add_f32_e32 v129, 1.0, v131
	v_mul_f32_e32 v131, 0x3e0293ee, v123
	v_log_f32_e32 v129, v129
	v_exp_f32_e32 v133, v131
	v_cmp_lt_f32_e32 vcc, s5, v130
	v_cndmask_b32_e64 v128, 0, -v229, s[52:53]
	v_add_f32_e32 v126, v128, v126
	v_cndmask_b32_e32 v230, v129, v130, vcc
	v_add_f32_e32 v129, 1.0, v133
	v_log_f32_e32 v129, v129
	v_cmp_lt_f32_e32 vcc, s5, v131
	v_cndmask_b32_e64 v130, 0, -v230, s[54:55]
	v_add_f32_e32 v126, v130, v126
	v_cndmask_b32_e32 v231, v129, v131, vcc
	v_cndmask_b32_e64 v129, 0, -v231, s[56:57]
	v_add_f32_e32 v232, v129, v126
	v_cvt_pk_bf16_f32 v126, v127, v128
	v_cvt_pk_bf16_f32 v127, v130, v129
	ds_write2_b64 v140, v[124:125], v[126:127] offset0:16 offset1:20
	s_waitcnt lgkmcnt(0)
; #define LAS __attribute__((address_space(3)))
; __device__ __forceinline__ unsigned pk2(float lo, float hi) { return pg8::cvt_pk_bf16(lo, hi); }
; __device__ __forceinline__ f32x4 mfma16(bf16x8 a, bf16x8 b, f32x4 c) { return __builtin_amdgcn_mfma_f32_16x16x32_bf16(a, b, c, 0, 0, 0); }
; #define LDS_FENCE() asm volatile("s_waitcnt lgkmcnt(0)" ::: "memory")
; template <bool DIAG, int NST>
; __device__ __forceinline__ void attn_tile(LAS unsigned char* lds, const bf16x8 (&qf)[4], f32x4 (&accO)[8], float& R, int w, int l15, int quad, int tl, bf16x8 U1, bf16x8 T0, bf16x8 T1) {
;     ...
;     { bf16x8 bb[4];
; #pragma unroll
;       for (int kj = 0; kj < NST / 2; ++kj) bb[kj] = *(const LAS bf16x8*)(lds + AT_P + tl * 272 + (32 * kj + 8 * quad) * 2);
;       rs += __shfl_xor(rs, 16); rs += __shfl_xor(rs, 32);
; #pragma unroll
;       for (int st = 0; st < NST; ++st) {
;           u32x2 wv = {0u, 0u};
;           if (true) {
;               f32x4 cs = (f32x4){0.f, 0.f, 0.f, 0.f};
; #pragma unroll
;               for (int kj = st >> 1; kj < NST / 2; ++kj) { const int dd = 2 * kj - st; cs = mfma16(dd == 0 ? T0 : (dd == -1 ? T1 : U1), bb[kj], cs); }
;               float a[4];
; #pragma unroll
;               for (int j = 0; j < 4; ++j) { float av = __builtin_amdgcn_exp2f(z[st][j] + cs[j] + R);
;                   if (DIAG) { const int s = 16 * st + 4 * quad + j; av = (s < tl) ? av : 0.f; }
;                   a[j] = av; }
;               wv.x = pk2(a[0], a[1]); wv.y = pk2(a[2], a[3]); }
;           *(LAS u32x2*)(lds + AT_P + tl * 272 + (16 * st + 4 * quad) * 2) = wv; } }
;     R += rs;
;     LDS_FENCE();
	ds_read_b128 v[124:127], v167
	ds_read_b128 v[128:131], v167 offset:64
	ds_read_b128 v[146:149], v167 offset:128
	s_mov_b32 s78, s76
	s_mov_b32 s79, s76
	s_mov_b32 s77, s76
	v_mov_b64_e32 v[152:153], s[78:79]
	v_mov_b64_e32 v[150:151], s[76:77]
	s_waitcnt lgkmcnt(2)
	v_mfma_f32_16x16x32_bf16 v[214:217], v[4:7], v[124:127], 0
	v_and_b32_e32 v134, 64, v206
	v_xor_b32_e32 v133, 16, v206
	v_add_u32_e32 v233, 64, v134
	v_mfma_f32_16x16x32_bf16 v[124:127], v[0:3], v[124:127], 0
	v_cmp_lt_i32_e32 vcc, v133, v233
	v_fma_f32 v120, v120, s88, -v228
	v_fma_f32 v123, v123, s88, -v231
	s_waitcnt lgkmcnt(1)
	v_mfma_f32_16x16x32_bf16 v[214:217], v[150:153], v[128:131], v[214:217]
	v_cndmask_b32_e32 v133, v206, v133, vcc
	v_lshlrev_b32_e32 v133, 2, v133
	ds_bpermute_b32 v234, v133, v232
	v_mfma_f32_16x16x32_bf16 v[124:127], v[150:153], v[128:131], v[124:127]
	v_fma_f32 v122, v122, s88, -v230
	v_fma_f32 v121, v121, s88, -v229
	s_mov_b64 s[78:79], 0
	s_waitcnt lgkmcnt(1)
	v_mfma_f32_16x16x32_bf16 v[214:217], v[150:153], v[146:149], v[214:217]
	v_mfma_f32_16x16x32_bf16 v[124:127], v[150:153], v[146:149], v[124:127]
	s_nop 6
	v_add_f32_e32 v133, v144, v214
	v_add_f32_e32 v134, v141, v215
	v_add_f32_e32 v133, v165, v133
	v_add_f32_e32 v134, v165, v134
	v_add_f32_e32 v124, v136, v124
	v_exp_f32_e32 v133, v133
	v_exp_f32_e32 v134, v134
	v_add_f32_e32 v135, v142, v216
	v_add_f32_e32 v141, v143, v217
	v_add_f32_e32 v124, v165, v124
	v_add_f32_e32 v135, v165, v135
	v_add_f32_e32 v141, v165, v141
	v_exp_f32_e32 v124, v124
	v_exp_f32_e32 v135, v135
	v_exp_f32_e32 v141, v141
	v_cndmask_b32_e64 v133, 0, v133, s[8:9]
	v_cndmask_b32_e64 v134, 0, v134, s[10:11]
	v_cvt_pk_bf16_f32 v134, v133, v134
	v_cndmask_b32_e64 v133, 0, v124, s[16:17]
	v_add_f32_e32 v124, v137, v125
	v_cndmask_b32_e64 v135, 0, v135, s[12:13]
	v_cndmask_b32_e64 v136, 0, v141, s[14:15]
	v_add_f32_e32 v124, v165, v124
	v_cvt_pk_bf16_f32 v135, v135, v136
	v_exp_f32_e32 v136, v124
	v_add_f32_e32 v124, v138, v126
	v_add_f32_e32 v124, v165, v124
	v_exp_f32_e32 v137, v124
	v_add_f32_e32 v124, v139, v127
	v_add_f32_e32 v124, v165, v124
	v_exp_f32_e32 v138, v124
	v_mfma_f32_16x16x32_bf16 v[124:127], v[4:7], v[128:131], 0
	v_cndmask_b32_e64 v136, 0, v136, s[18:19]
	v_cndmask_b32_e64 v137, 0, v137, s[20:21]
	v_cndmask_b32_e64 v138, 0, v138, s[22:23]
	v_mfma_f32_16x16x32_bf16 v[124:127], v[150:153], v[146:149], v[124:127]
	s_nop 7
	v_add_f32_e32 v124, v132, v124
	v_add_f32_e32 v124, v165, v124
	v_exp_f32_e32 v124, v124
	v_cvt_pk_bf16_f32 v132, v133, v136
	v_cvt_pk_bf16_f32 v133, v137, v138
	ds_write2_b64 v140, v[134:135], v[132:133] offset1:4
	v_cndmask_b32_e64 v132, 0, v124, s[24:25]
	v_add_f32_e32 v124, v154, v125
	v_add_f32_e32 v125, v155, v126
	v_add_f32_e32 v124, v165, v124
	v_add_f32_e32 v125, v165, v125
	v_exp_f32_e32 v124, v124
	v_exp_f32_e32 v125, v125
	v_add_f32_e32 v126, v218, v127
	v_add_f32_e32 v126, v165, v126
	v_exp_f32_e32 v133, v126
	v_cndmask_b32_e64 v134, 0, v124, s[26:27]
	v_cndmask_b32_e64 v135, 0, v125, s[28:29]
	v_mfma_f32_16x16x32_bf16 v[124:127], v[0:3], v[128:131], 0
	v_cndmask_b32_e64 v129, 0, v133, s[30:31]
	v_cvt_pk_bf16_f32 v128, v132, v134
	v_cvt_pk_bf16_f32 v129, v135, v129
	v_mfma_f32_16x16x32_bf16 v[124:127], v[150:153], v[146:149], v[124:127]
	v_xor_b32_e32 v130, 32, v206
	v_cmp_lt_i32_e32 vcc, v130, v233
	s_waitcnt lgkmcnt(1)
	v_add_f32_e32 v131, v232, v234
	v_cndmask_b32_e32 v130, v206, v130, vcc
	s_nop 2
	v_add_f32_e32 v124, v145, v124
	v_add_f32_e32 v125, v219, v125
	v_add_f32_e32 v126, v220, v126
	v_add_f32_e32 v127, v221, v127
	v_add_f32_e32 v124, v165, v124
	v_add_f32_e32 v125, v165, v125
	v_add_f32_e32 v126, v165, v126
	v_add_f32_e32 v127, v165, v127
	v_exp_f32_e32 v124, v124
	v_exp_f32_e32 v125, v125
	v_exp_f32_e32 v126, v126
	v_exp_f32_e32 v127, v127
	v_cndmask_b32_e64 v124, 0, v124, s[34:35]
	v_cndmask_b32_e64 v125, 0, v125, s[36:37]
	v_cndmask_b32_e64 v126, 0, v126, s[38:39]
	v_cndmask_b32_e64 v127, 0, v127, s[40:41]
	v_cvt_pk_bf16_f32 v124, v124, v125
	v_cvt_pk_bf16_f32 v125, v126, v127
	ds_write2_b64 v140, v[128:129], v[124:125] offset0:8 offset1:12
	v_mfma_f32_16x16x32_bf16 v[124:127], v[4:7], v[146:149], 0
	v_lshlrev_b32_e32 v130, 2, v130
	s_nop 6
	v_add_f32_e32 v124, v222, v124
	v_add_f32_e32 v125, v223, v125
	v_add_f32_e32 v126, v226, v126
	v_add_f32_e32 v127, v227, v127
	v_add_f32_e32 v124, v165, v124
	v_add_f32_e32 v125, v165, v125
	v_add_f32_e32 v126, v165, v126
	v_add_f32_e32 v127, v165, v127
	v_exp_f32_e32 v124, v124
	v_exp_f32_e32 v125, v125
	v_exp_f32_e32 v126, v126
	v_exp_f32_e32 v127, v127
	v_cndmask_b32_e64 v124, 0, v124, s[42:43]
	v_cndmask_b32_e64 v125, 0, v125, s[44:45]
	v_cndmask_b32_e64 v126, 0, v126, s[46:47]
	v_cndmask_b32_e64 v127, 0, v127, s[48:49]
	v_cvt_pk_bf16_f32 v128, v124, v125
	v_cvt_pk_bf16_f32 v129, v126, v127
	v_mfma_f32_16x16x32_bf16 v[124:127], v[0:3], v[146:149], 0
	s_nop 7
	v_add_f32_e32 v120, v120, v124
	v_add_f32_e32 v121, v121, v125
	v_add_f32_e32 v122, v122, v126
	v_add_f32_e32 v123, v123, v127
	v_add_f32_e32 v120, v165, v120
	v_add_f32_e32 v121, v165, v121
	v_add_f32_e32 v122, v165, v122
	v_add_f32_e32 v123, v165, v123
	v_exp_f32_e32 v120, v120
	v_exp_f32_e32 v121, v121
	v_exp_f32_e32 v122, v122
	v_exp_f32_e32 v123, v123
	v_cndmask_b32_e64 v120, 0, v120, s[50:51]
	v_cndmask_b32_e64 v121, 0, v121, s[52:53]
	v_cndmask_b32_e64 v122, 0, v122, s[54:55]
	v_cndmask_b32_e64 v123, 0, v123, s[56:57]
	ds_bpermute_b32 v124, v130, v131
	v_cvt_pk_bf16_f32 v120, v120, v121
	v_cvt_pk_bf16_f32 v121, v122, v123
	ds_write2_b64 v140, v[128:129], v[120:121] offset0:16 offset1:20
	s_waitcnt lgkmcnt(0)
	s_waitcnt lgkmcnt(1)
	v_add_f32_e32 v214, v131, v124

; #define LAS __attribute__((address_space(3)))
; __device__ __forceinline__ unsigned pk2(float lo, float hi) { return pg8::cvt_pk_bf16(lo, hi); }
; __device__ __forceinline__ f32x4 mfma16(bf16x8 a, bf16x8 b, f32x4 c) { return __builtin_amdgcn_mfma_f32_16x16x32_bf16(a, b, c, 0, 0, 0); }
; template <bool DIAG, int NST>
; __device__ __forceinline__ void attn_tile(LAS unsigned char* lds, const bf16x8 (&qf)[4], f32x4 (&accO)[8], float& R, int w, int l15, int quad, int tl, bf16x8 U1, bf16x8 T0, bf16x8 T1) {
;     ...
;     f32x4 z[8];
; #pragma unroll
;     for (int st = 0; st < NST; ++st) { z[st] = (f32x4){0.f, 0.f, 0.f, 0.f};
;         if (true) {
; #pragma unroll
;             for (int ks = 0; ks < 4; ++ks) { const bf16x8 a = *(const LAS bf16x8*)(lds + AT_KS + (16 * st + l15) * 272 + (32 * ks + 8 * quad) * 2); z[st] = mfma16(a, qf[ks], z[st]); } }
;         if (st & 1) __builtin_amdgcn_sched_barrier(0); }
;     float rs = 0.f;
; #pragma unroll
;     for (int st = 0; st < NST; ++st) {
;         u32x2 wv = {0u, 0u};
;         if (true) { float lk[4];
; #pragma unroll
;             for (int j = 0; j < 4; ++j) { const float z2 = z[st][j] * SCALE2; float sp = __builtin_amdgcn_logf(1.0f + __builtin_amdgcn_exp2f(z2)); sp = (z2 > 64.0f) ? z2 : sp;
;                 if (DIAG) { const int s = 16 * st + 4 * quad + j; lk[j] = (s < tl) ? -sp : 0.f; } else lk[j] = -sp;
;                 z[st][j] = z2 - sp; rs += lk[j]; }
;             wv.x = pk2(lk[0], lk[1]); wv.y = pk2(lk[2], lk[3]); }
;         *(LAS u32x2*)(lds + AT_P + tl * 272 + (16 * st + 4 * quad) * 2) = wv;
.LBB0_993:
	s_waitcnt lgkmcnt(7)
	v_mfma_f32_16x16x32_bf16 v[120:123], v[88:91], v[24:27], 0
	s_waitcnt lgkmcnt(6)
	v_mfma_f32_16x16x32_bf16 v[120:123], v[92:95], v[28:31], v[120:123]
	s_waitcnt lgkmcnt(5)
	v_mfma_f32_16x16x32_bf16 v[120:123], v[96:99], v[32:35], v[120:123]
	s_waitcnt lgkmcnt(4)
	v_mfma_f32_16x16x32_bf16 v[148:151], v[100:103], v[36:39], v[120:123]
	s_waitcnt lgkmcnt(3)
	v_mfma_f32_16x16x32_bf16 v[120:123], v[104:107], v[24:27], 0
	s_waitcnt lgkmcnt(2)
	v_mfma_f32_16x16x32_bf16 v[120:123], v[108:111], v[28:31], v[120:123]
	s_waitcnt lgkmcnt(1)
	v_mfma_f32_16x16x32_bf16 v[120:123], v[112:115], v[32:35], v[120:123]
	s_waitcnt lgkmcnt(0)
	v_mfma_f32_16x16x32_bf16 v[144:147], v[116:119], v[36:39], v[120:123]
	s_nop 5
	ds_read_b128 v[120:123], v173 offset:8704
	ds_read_b128 v[124:127], v173 offset:8768
	s_waitcnt lgkmcnt(1)
	v_mfma_f32_16x16x32_bf16 v[120:123], v[120:123], v[24:27], 0
	s_waitcnt lgkmcnt(0)
	v_mfma_f32_16x16x32_bf16 v[120:123], v[124:127], v[28:31], v[120:123]
	ds_read_b128 v[124:127], v173 offset:8832
	s_waitcnt lgkmcnt(0)
	v_mfma_f32_16x16x32_bf16 v[120:123], v[124:127], v[32:35], v[120:123]
	ds_read_b128 v[124:127], v173 offset:8896
	s_waitcnt lgkmcnt(0)
	v_mfma_f32_16x16x32_bf16 v[140:143], v[124:127], v[36:39], v[120:123]
	s_nop 4
	ds_read_b128 v[120:123], v173 offset:13056
	ds_read_b128 v[124:127], v173 offset:13120
	s_waitcnt lgkmcnt(1)
	v_mfma_f32_16x16x32_bf16 v[120:123], v[120:123], v[24:27], 0
	s_waitcnt lgkmcnt(0)
	v_mfma_f32_16x16x32_bf16 v[120:123], v[124:127], v[28:31], v[120:123]
	ds_read_b128 v[124:127], v173 offset:13184
	s_waitcnt lgkmcnt(0)
	v_mfma_f32_16x16x32_bf16 v[120:123], v[124:127], v[32:35], v[120:123]
	ds_read_b128 v[124:127], v173 offset:13248
	s_waitcnt lgkmcnt(0)
	v_mfma_f32_16x16x32_bf16 v[136:139], v[124:127], v[36:39], v[120:123]
	s_nop 4
	ds_read_b128 v[120:123], v173 offset:17408
	ds_read_b128 v[124:127], v173 offset:17472
	s_waitcnt lgkmcnt(1)
	v_mfma_f32_16x16x32_bf16 v[120:123], v[120:123], v[24:27], 0
	s_waitcnt lgkmcnt(0)
	v_mfma_f32_16x16x32_bf16 v[120:123], v[124:127], v[28:31], v[120:123]
	ds_read_b128 v[124:127], v173 offset:17536
	s_waitcnt lgkmcnt(0)
	v_mfma_f32_16x16x32_bf16 v[120:123], v[124:127], v[32:35], v[120:123]
	ds_read_b128 v[124:127], v173 offset:17600
	s_waitcnt lgkmcnt(0)
	v_mfma_f32_16x16x32_bf16 v[132:135], v[124:127], v[36:39], v[120:123]
	s_nop 4
	ds_read_b128 v[120:123], v173 offset:21760
	ds_read_b128 v[124:127], v173 offset:21824
	s_waitcnt lgkmcnt(1)
	v_mfma_f32_16x16x32_bf16 v[120:123], v[120:123], v[24:27], 0
	s_waitcnt lgkmcnt(0)
	v_mfma_f32_16x16x32_bf16 v[120:123], v[124:127], v[28:31], v[120:123]
	ds_read_b128 v[124:127], v173 offset:21888
	s_waitcnt lgkmcnt(0)
	v_mfma_f32_16x16x32_bf16 v[120:123], v[124:127], v[32:35], v[120:123]
	ds_read_b128 v[124:127], v173 offset:21952
	s_waitcnt lgkmcnt(0)
	v_mfma_f32_16x16x32_bf16 v[128:131], v[124:127], v[36:39], v[120:123]
	s_nop 4
	ds_read_b128 v[120:123], v173 offset:26112
	ds_read_b128 v[124:127], v173 offset:26176
	s_waitcnt lgkmcnt(1)
	v_mfma_f32_16x16x32_bf16 v[120:123], v[120:123], v[24:27], 0
	ds_read_b128 v[152:155], v173 offset:30528
	s_waitcnt lgkmcnt(1)
	v_mfma_f32_16x16x32_bf16 v[120:123], v[124:127], v[28:31], v[120:123]
	ds_read_b128 v[124:127], v173 offset:26240
	s_waitcnt lgkmcnt(0)
	v_mfma_f32_16x16x32_bf16 v[120:123], v[124:127], v[32:35], v[120:123]
	ds_read_b128 v[124:127], v173 offset:26304
	s_waitcnt lgkmcnt(0)
	v_mfma_f32_16x16x32_bf16 v[124:127], v[124:127], v[36:39], v[120:123]
	s_nop 4
	ds_read_b128 v[120:123], v173 offset:30464
	s_waitcnt lgkmcnt(0)
	v_mfma_f32_16x16x32_bf16 v[120:123], v[120:123], v[24:27], 0
	v_mfma_f32_16x16x32_bf16 v[120:123], v[152:155], v[28:31], v[120:123]
	ds_read_b128 v[152:155], v173 offset:30592
	s_waitcnt lgkmcnt(0)
	v_mfma_f32_16x16x32_bf16 v[120:123], v[152:155], v[32:35], v[120:123]
	ds_read_b128 v[152:155], v173 offset:30656
	s_waitcnt lgkmcnt(0)
	v_mfma_f32_16x16x32_bf16 v[120:123], v[152:155], v[36:39], v[120:123]
	v_mul_f32_e32 v152, 0x3e0293ee, v148
	v_exp_f32_e32 v153, v152
	v_cmp_lt_f32_e32 vcc, s5, v152
	v_add_f32_e32 v153, 1.0, v153
	v_log_f32_e32 v153, v153
	s_nop 0
	v_cndmask_b32_e32 v152, v153, v152, vcc
	v_cndmask_b32_e64 v153, 0, -v152, s[8:9]
	v_fma_f32 v152, v148, s88, -v152
	v_mul_f32_e32 v148, 0x3e0293ee, v149
	v_exp_f32_e32 v154, v148
	v_cmp_lt_f32_e32 vcc, s5, v148
	v_add_f32_e32 v154, 1.0, v154
	v_log_f32_e32 v154, v154
	s_nop 0
	v_cndmask_b32_e32 v148, v154, v148, vcc
	v_cndmask_b32_e64 v214, 0, -v148, s[10:11]
	v_fma_f32 v149, v149, s88, -v148
	v_mul_f32_e32 v148, 0x3e0293ee, v150
	v_exp_f32_e32 v154, v148
	v_cmp_lt_f32_e32 vcc, s5, v148
	v_add_f32_e32 v154, 1.0, v154
	v_log_f32_e32 v154, v154
	s_nop 0
	v_cndmask_b32_e32 v148, v154, v148, vcc
	v_cndmask_b32_e64 v215, 0, -v148, s[12:13]
	v_fma_f32 v150, v150, s88, -v148
	v_mul_f32_e32 v148, 0x3e0293ee, v151
	v_exp_f32_e32 v154, v148
	v_cmp_lt_f32_e32 vcc, s5, v148
	v_add_f32_e32 v154, 1.0, v154
	v_log_f32_e32 v154, v154
	s_nop 0
	v_cndmask_b32_e32 v148, v154, v148, vcc
	v_cvt_pk_bf16_f32 v154, v153, v214
	v_add_f32_e32 v153, 0, v153
	v_cndmask_b32_e64 v216, 0, -v148, s[14:15]
	v_add_f32_e32 v153, v214, v153
	v_mul_f32_e32 v214, 0x3e0293ee, v144
	v_cvt_pk_bf16_f32 v155, v215, v216
	v_add_f32_e32 v153, v215, v153
	v_exp_f32_e32 v215, v214
	v_cmp_lt_f32_e32 vcc, s5, v214
	v_add_f32_e32 v153, v216, v153
	v_fma_f32 v151, v151, s88, -v148
	v_add_f32_e32 v215, 1.0, v215
	v_log_f32_e32 v215, v215
	v_add_u32_e32 v148, v174, v158
	v_cndmask_b32_e32 v214, v215, v214, vcc
	v_cndmask_b32_e64 v215, 0, -v214, s[16:17]
	v_fma_f32 v144, v144, s88, -v214
	v_mul_f32_e32 v214, 0x3e0293ee, v145
; #define LAS __attribute__((address_space(3)))
; __device__ __forceinline__ unsigned pk2(float lo, float hi) { return pg8::cvt_pk_bf16(lo, hi); }
; template <bool DIAG, int NST>
; __device__ __forceinline__ void attn_tile(LAS unsigned char* lds, const bf16x8 (&qf)[4], f32x4 (&accO)[8], float& R, int w, int l15, int quad, int tl, bf16x8 U1, bf16x8 T0, bf16x8 T1) {
;     ...
;     for (int st = 0; st < NST; ++st) {
;         u32x2 wv = {0u, 0u};
;         if (true) { float lk[4];
; #pragma unroll
;             for (int j = 0; j < 4; ++j) { const float z2 = z[st][j] * SCALE2; float sp = __builtin_amdgcn_logf(1.0f + __builtin_amdgcn_exp2f(z2)); sp = (z2 > 64.0f) ? z2 : sp;
;                 if (DIAG) { const int s = 16 * st + 4 * quad + j; lk[j] = (s < tl) ? -sp : 0.f; } else lk[j] = -sp;
;                 z[st][j] = z2 - sp; rs += lk[j]; }
;             wv.x = pk2(lk[0], lk[1]); wv.y = pk2(lk[2], lk[3]); }
;         *(LAS u32x2*)(lds + AT_P + tl * 272 + (16 * st + 4 * quad) * 2) = wv;
;         if (st & 1) __builtin_amdgcn_sched_barrier(0); }
	v_exp_f32_e32 v216, v214
	v_cmp_lt_f32_e32 vcc, s5, v214
	v_add_f32_e32 v153, v153, v215
	v_add_f32_e32 v216, 1.0, v216
	v_log_f32_e32 v216, v216
	s_nop 0
	v_cndmask_b32_e32 v214, v216, v214, vcc
	v_cndmask_b32_e64 v216, 0, -v214, s[18:19]
	v_fma_f32 v145, v145, s88, -v214
	v_mul_f32_e32 v214, 0x3e0293ee, v146
	v_exp_f32_e32 v217, v214
	v_cmp_lt_f32_e32 vcc, s5, v214
	v_add_f32_e32 v153, v216, v153
	v_add_f32_e32 v217, 1.0, v217
	v_log_f32_e32 v217, v217
	s_nop 0
	v_cndmask_b32_e32 v214, v217, v214, vcc
	v_cndmask_b32_e64 v217, 0, -v214, s[20:21]
	v_fma_f32 v146, v146, s88, -v214
	v_mul_f32_e32 v214, 0x3e0293ee, v147
	v_exp_f32_e32 v218, v214
	v_cmp_lt_f32_e32 vcc, s5, v214
	v_add_f32_e32 v153, v217, v153
	v_add_f32_e32 v218, 1.0, v218
	v_log_f32_e32 v218, v218
	s_nop 0
	v_cndmask_b32_e32 v214, v218, v214, vcc
	v_cndmask_b32_e64 v218, 0, -v214, s[22:23]
	v_fma_f32 v147, v147, s88, -v214
	v_cvt_pk_bf16_f32 v214, v215, v216
	v_cvt_pk_bf16_f32 v215, v217, v218
	v_add_f32_e32 v153, v218, v153
	ds_write2_b64 v148, v[154:155], v[214:215] offset1:4
	v_mul_f32_e32 v154, 0x3e0293ee, v140
	v_exp_f32_e32 v155, v154
	v_cmp_lt_f32_e32 vcc, s5, v154
	v_add_f32_e32 v155, 1.0, v155
	v_log_f32_e32 v155, v155
	s_nop 0
	v_cndmask_b32_e32 v154, v155, v154, vcc
	v_cndmask_b32_e64 v214, 0, -v154, s[24:25]
	v_fma_f32 v140, v140, s88, -v154
	v_mul_f32_e32 v154, 0x3e0293ee, v141
	v_exp_f32_e32 v155, v154
	v_cmp_lt_f32_e32 vcc, s5, v154
	v_add_f32_e32 v153, v153, v214
	v_add_f32_e32 v155, 1.0, v155
	v_log_f32_e32 v155, v155
	s_nop 0
	v_cndmask_b32_e32 v154, v155, v154, vcc
	v_cndmask_b32_e64 v215, 0, -v154, s[26:27]
	v_fma_f32 v141, v141, s88, -v154
	v_mul_f32_e32 v154, 0x3e0293ee, v142
	v_exp_f32_e32 v155, v154
	v_cmp_lt_f32_e32 vcc, s5, v154
	v_add_f32_e32 v153, v215, v153
	v_add_f32_e32 v155, 1.0, v155
	v_log_f32_e32 v155, v155
	s_nop 0
	v_cndmask_b32_e32 v154, v155, v154, vcc
	v_cndmask_b32_e64 v216, 0, -v154, s[28:29]
	v_fma_f32 v142, v142, s88, -v154
	v_mul_f32_e32 v154, 0x3e0293ee, v143
	v_exp_f32_e32 v155, v154
	v_cmp_lt_f32_e32 vcc, s5, v154
	v_add_f32_e32 v153, v216, v153
	v_add_f32_e32 v155, 1.0, v155
	v_log_f32_e32 v155, v155
	s_nop 0
	v_cndmask_b32_e32 v154, v155, v154, vcc
	v_cndmask_b32_e64 v217, 0, -v154, s[30:31]
	v_fma_f32 v143, v143, s88, -v154
	v_cvt_pk_bf16_f32 v154, v214, v215
	v_mul_f32_e32 v214, 0x3e0293ee, v136
	v_exp_f32_e32 v215, v214
	v_cmp_lt_f32_e32 vcc, s5, v214
	v_cvt_pk_bf16_f32 v155, v216, v217
	v_add_f32_e32 v153, v217, v153
	v_add_f32_e32 v215, 1.0, v215
	v_log_f32_e32 v215, v215
	s_nop 0
	v_cndmask_b32_e32 v214, v215, v214, vcc
	v_cndmask_b32_e64 v215, 0, -v214, s[34:35]
	v_fma_f32 v136, v136, s88, -v214
	v_mul_f32_e32 v214, 0x3e0293ee, v137
	v_exp_f32_e32 v216, v214
	v_cmp_lt_f32_e32 vcc, s5, v214
	v_add_f32_e32 v153, v153, v215
	v_add_f32_e32 v216, 1.0, v216
	v_log_f32_e32 v216, v216
	s_nop 0
	v_cndmask_b32_e32 v214, v216, v214, vcc
	v_cndmask_b32_e64 v216, 0, -v214, s[36:37]
	v_fma_f32 v137, v137, s88, -v214
	v_mul_f32_e32 v214, 0x3e0293ee, v138
	v_exp_f32_e32 v217, v214
	v_cmp_lt_f32_e32 vcc, s5, v214
	v_add_f32_e32 v153, v216, v153
	v_add_f32_e32 v217, 1.0, v217
	v_log_f32_e32 v217, v217
	s_nop 0
	v_cndmask_b32_e32 v214, v217, v214, vcc
	v_cndmask_b32_e64 v217, 0, -v214, s[38:39]
	v_fma_f32 v138, v138, s88, -v214
	v_mul_f32_e32 v214, 0x3e0293ee, v139
	v_exp_f32_e32 v218, v214
	v_cmp_lt_f32_e32 vcc, s5, v214
	v_add_f32_e32 v153, v217, v153
	v_add_f32_e32 v218, 1.0, v218
	v_log_f32_e32 v218, v218
	s_nop 0
	v_cndmask_b32_e32 v214, v218, v214, vcc
	v_cndmask_b32_e64 v218, 0, -v214, s[40:41]
	v_fma_f32 v139, v139, s88, -v214
	v_cvt_pk_bf16_f32 v214, v215, v216
	v_cvt_pk_bf16_f32 v215, v217, v218
	v_add_f32_e32 v153, v218, v153
	ds_write2_b64 v148, v[154:155], v[214:215] offset0:8 offset1:12
	v_mul_f32_e32 v154, 0x3e0293ee, v132
	v_exp_f32_e32 v155, v154
	v_cmp_lt_f32_e32 vcc, s5, v154
	v_add_f32_e32 v155, 1.0, v155
	v_log_f32_e32 v155, v155
	s_nop 0
	v_cndmask_b32_e32 v154, v155, v154, vcc
	v_cndmask_b32_e64 v155, 0, -v154, s[42:43]
	v_fma_f32 v132, v132, s88, -v154
	v_mul_f32_e32 v154, 0x3e0293ee, v133
	v_exp_f32_e32 v214, v154
	v_cmp_lt_f32_e32 vcc, s5, v154
	v_add_f32_e32 v153, v153, v155
	v_add_f32_e32 v214, 1.0, v214
	v_log_f32_e32 v214, v214
	s_nop 0
	v_cndmask_b32_e32 v154, v214, v154, vcc
	v_cndmask_b32_e64 v214, 0, -v154, s[44:45]
	v_fma_f32 v133, v133, s88, -v154
	v_mul_f32_e32 v154, 0x3e0293ee, v134
	v_exp_f32_e32 v215, v154
	v_cmp_lt_f32_e32 vcc, s5, v154
	v_add_f32_e32 v153, v214, v153
	v_add_f32_e32 v215, 1.0, v215
	v_log_f32_e32 v215, v215
	s_nop 0
	v_cndmask_b32_e32 v154, v215, v154, vcc
	v_cndmask_b32_e64 v215, 0, -v154, s[46:47]
	v_fma_f32 v154, v134, s88, -v154
	v_mul_f32_e32 v134, 0x3e0293ee, v135
	v_exp_f32_e32 v216, v134
	v_cmp_lt_f32_e32 vcc, s5, v134
	v_add_f32_e32 v153, v215, v153
	v_add_f32_e32 v216, 1.0, v216
	v_log_f32_e32 v216, v216
	s_nop 0
	v_cndmask_b32_e32 v134, v216, v134, vcc
	v_cndmask_b32_e64 v216, 0, -v134, s[48:49]
	v_fma_f32 v222, v135, s88, -v134
	v_cvt_pk_bf16_f32 v134, v155, v214
	v_mul_f32_e32 v155, 0x3e0293ee, v128
	v_exp_f32_e32 v214, v155
	v_cmp_lt_f32_e32 vcc, s5, v155
	v_add_f32_e32 v153, v216, v153
	v_cvt_pk_bf16_f32 v135, v215, v216
	v_add_f32_e32 v214, 1.0, v214
	v_log_f32_e32 v214, v214
	s_nop 0
	v_cndmask_b32_e32 v155, v214, v155, vcc
	v_cndmask_b32_e64 v214, 0, -v155, s[50:51]
	v_fma_f32 v155, v128, s88, -v155
	v_add_f32_e32 v128, v153, v214
	v_mul_f32_e32 v153, 0x3e0293ee, v129
	v_exp_f32_e32 v215, v153
	v_cmp_lt_f32_e32 vcc, s5, v153
	v_add_f32_e32 v215, 1.0, v215
	v_log_f32_e32 v215, v215
	s_nop 0
	v_cndmask_b32_e32 v153, v215, v153, vcc
	v_cndmask_b32_e64 v215, 0, -v153, s[52:53]
; #define LAS __attribute__((address_space(3)))
; __device__ __forceinline__ unsigned pk2(float lo, float hi) { return pg8::cvt_pk_bf16(lo, hi); }
; __device__ __forceinline__ f32x4 mfma16(bf16x8 a, bf16x8 b, f32x4 c) { return __builtin_amdgcn_mfma_f32_16x16x32_bf16(a, b, c, 0, 0, 0); }
; #define LDS_FENCE() asm volatile("s_waitcnt lgkmcnt(0)" ::: "memory")
; template <bool DIAG, int NST>
; __device__ __forceinline__ void attn_tile(LAS unsigned char* lds, const bf16x8 (&qf)[4], f32x4 (&accO)[8], float& R, int w, int l15, int quad, int tl, bf16x8 U1, bf16x8 T0, bf16x8 T1) {
;     ...
;     for (int st = 0; st < NST; ++st) {
;         u32x2 wv = {0u, 0u};
;         if (true) { float lk[4];
; #pragma unroll
;             for (int j = 0; j < 4; ++j) { const float z2 = z[st][j] * SCALE2; float sp = __builtin_amdgcn_logf(1.0f + __builtin_amdgcn_exp2f(z2)); sp = (z2 > 64.0f) ? z2 : sp;
;                 if (DIAG) { const int s = 16 * st + 4 * quad + j; lk[j] = (s < tl) ? -sp : 0.f; } else lk[j] = -sp;
;                 z[st][j] = z2 - sp; rs += lk[j]; }
;             wv.x = pk2(lk[0], lk[1]); wv.y = pk2(lk[2], lk[3]); }
;         *(LAS u32x2*)(lds + AT_P + tl * 272 + (16 * st + 4 * quad) * 2) = wv;
;         if (st & 1) __builtin_amdgcn_sched_barrier(0); }
;     LDS_FENCE();
;     { bf16x8 bb[4];
; #pragma unroll
;       for (int kj = 0; kj < NST / 2; ++kj) bb[kj] = *(const LAS bf16x8*)(lds + AT_P + tl * 272 + (32 * kj + 8 * quad) * 2);
;       rs += __shfl_xor(rs, 16); rs += __shfl_xor(rs, 32);
; #pragma unroll
;       for (int st = 0; st < NST; ++st) {
;           u32x2 wv = {0u, 0u};
;           if (true) {
;               f32x4 cs = (f32x4){0.f, 0.f, 0.f, 0.f};
; #pragma unroll
;               for (int kj = st >> 1; kj < NST / 2; ++kj) { const int dd = 2 * kj - st; cs = mfma16(dd == 0 ? T0 : (dd == -1 ? T1 : U1), bb[kj], cs); }
	v_fma_f32 v153, v129, s88, -v153
	v_mul_f32_e32 v129, 0x3e0293ee, v130
	v_exp_f32_e32 v216, v129
	v_cmp_lt_f32_e32 vcc, s5, v129
	v_add_f32_e32 v128, v215, v128
	v_add_f32_e32 v216, 1.0, v216
	v_log_f32_e32 v216, v216
	s_nop 0
	v_cndmask_b32_e32 v129, v216, v129, vcc
	v_cndmask_b32_e64 v216, 0, -v129, s[54:55]
	v_fma_f32 v223, v130, s88, -v129
	v_mul_f32_e32 v129, 0x3e0293ee, v131
	v_exp_f32_e32 v130, v129
	v_cmp_lt_f32_e32 vcc, s5, v129
	v_add_f32_e32 v128, v216, v128
	v_add_f32_e32 v130, 1.0, v130
	v_log_f32_e32 v130, v130
	s_nop 0
	v_cndmask_b32_e32 v129, v130, v129, vcc
	v_cndmask_b32_e64 v130, 0, -v129, s[56:57]
	v_fma_f32 v234, v131, s88, -v129
	v_add_f32_e32 v131, v130, v128
	v_cvt_pk_bf16_f32 v128, v214, v215
	v_cvt_pk_bf16_f32 v129, v216, v130
	ds_write2_b64 v148, v[134:135], v[128:129] offset0:16 offset1:20
	v_mul_f32_e32 v128, 0x3e0293ee, v124
	v_exp_f32_e32 v129, v128
	v_mul_f32_e32 v130, 0x3e0293ee, v125
	v_exp_f32_e32 v134, v130
	v_cmp_lt_f32_e32 vcc, s5, v128
	v_add_f32_e32 v129, 1.0, v129
	v_log_f32_e32 v129, v129
	v_add_f32_e32 v134, 1.0, v134
	v_log_f32_e32 v134, v134
	v_mul_f32_e32 v135, 0x3e0293ee, v127
	v_cndmask_b32_e32 v128, v129, v128, vcc
	v_fma_f32 v235, v124, s88, -v128
	v_mul_f32_e32 v124, 0x3e0293ee, v126
	v_cndmask_b32_e64 v129, 0, -v128, s[58:59]
	v_exp_f32_e32 v128, v124
	v_exp_f32_e32 v214, v135
	v_cmp_lt_f32_e32 vcc, s5, v130
	v_add_f32_e32 v128, 1.0, v128
	s_nop 0
	v_cndmask_b32_e32 v130, v134, v130, vcc
	v_log_f32_e32 v128, v128
	v_fma_f32 v236, v125, s88, -v130
	v_add_f32_e32 v125, 1.0, v214
	v_log_f32_e32 v125, v125
	v_cmp_lt_f32_e32 vcc, s5, v124
	v_cndmask_b32_e64 v134, 0, -v130, s[60:61]
	s_nop 0
	v_cndmask_b32_e32 v124, v128, v124, vcc
	v_cmp_lt_f32_e32 vcc, s5, v135
	v_cndmask_b32_e64 v128, 0, -v124, s[62:63]
	v_fma_f32 v237, v126, s88, -v124
	v_cndmask_b32_e32 v124, v125, v135, vcc
	v_cndmask_b32_e64 v126, 0, -v124, s[64:65]
	v_fma_f32 v238, v127, s88, -v124
	v_cvt_pk_bf16_f32 v124, v129, v134
	v_add_f32_e32 v127, v131, v129
	v_mul_f32_e32 v129, 0x3e0293ee, v120
	v_exp_f32_e32 v130, v129
	v_add_f32_e32 v127, v134, v127
	v_add_f32_e32 v127, v128, v127
	v_cvt_pk_bf16_f32 v125, v128, v126
	v_add_f32_e32 v126, v126, v127
	v_add_f32_e32 v127, 1.0, v130
	v_mul_f32_e32 v128, 0x3e0293ee, v121
	v_log_f32_e32 v127, v127
	v_exp_f32_e32 v130, v128
	v_cmp_lt_f32_e32 vcc, s5, v129
	s_nop 1
	v_cndmask_b32_e32 v239, v127, v129, vcc
	v_add_f32_e32 v129, 1.0, v130
	v_mul_f32_e32 v130, 0x3e0293ee, v122
	v_log_f32_e32 v129, v129
	v_exp_f32_e32 v131, v130
	v_cmp_lt_f32_e32 vcc, s5, v128
	v_cndmask_b32_e64 v127, 0, -v239, s[66:67]
	v_add_f32_e32 v126, v126, v127
	v_cndmask_b32_e32 v240, v129, v128, vcc
	v_add_f32_e32 v129, 1.0, v131
	v_mul_f32_e32 v131, 0x3e0293ee, v123
	v_log_f32_e32 v129, v129
	v_exp_f32_e32 v134, v131
	v_cmp_lt_f32_e32 vcc, s5, v130
	v_cndmask_b32_e64 v128, 0, -v240, s[68:69]
	v_add_f32_e32 v126, v128, v126
	v_cndmask_b32_e32 v241, v129, v130, vcc
	v_add_f32_e32 v129, 1.0, v134
	v_log_f32_e32 v129, v129
	v_cmp_lt_f32_e32 vcc, s5, v131
	v_cndmask_b32_e64 v130, 0, -v241, s[70:71]
	v_add_f32_e32 v126, v130, v126
	v_cndmask_b32_e32 v242, v129, v131, vcc
	v_cndmask_b32_e64 v129, 0, -v242, s[72:73]
	v_add_f32_e32 v243, v129, v126
	v_cvt_pk_bf16_f32 v126, v127, v128
	v_cvt_pk_bf16_f32 v127, v130, v129
	ds_write2_b64 v148, v[124:125], v[126:127] offset0:24 offset1:28
	s_waitcnt lgkmcnt(0)
	ds_read_b128 v[124:127], v167
	ds_read_b128 v[128:131], v167 offset:64
	s_mov_b32 s78, s76
	s_mov_b32 s79, s76
	s_mov_b32 s77, s76
	v_mov_b64_e32 v[220:221], s[78:79]
	v_mov_b64_e32 v[218:219], s[76:77]
	s_waitcnt lgkmcnt(1)
	v_mfma_f32_16x16x32_bf16 v[214:217], v[4:7], v[124:127], 0
	ds_read_b128 v[226:229], v167 offset:128
	ds_read_b128 v[230:233], v167 offset:192
	v_and_b32_e32 v135, 64, v206
	v_mfma_f32_16x16x32_bf16 v[124:127], v[0:3], v[124:127], 0
	v_xor_b32_e32 v134, 16, v206
	v_add_u32_e32 v244, 64, v135
	v_cmp_lt_i32_e32 vcc, v134, v244
	s_waitcnt lgkmcnt(2)
	v_mfma_f32_16x16x32_bf16 v[214:217], v[218:221], v[128:131], v[214:217]
	v_fma_f32 v120, v120, s88, -v239
	v_cndmask_b32_e32 v134, v206, v134, vcc
	v_lshlrev_b32_e32 v134, 2, v134
	v_mfma_f32_16x16x32_bf16 v[124:127], v[218:221], v[128:131], v[124:127]
	ds_bpermute_b32 v245, v134, v243
	v_fma_f32 v123, v123, s88, -v242
	v_fma_f32 v122, v122, s88, -v241
	s_waitcnt lgkmcnt(2)
	v_mfma_f32_16x16x32_bf16 v[214:217], v[218:221], v[226:229], v[214:217]
	v_fma_f32 v121, v121, s88, -v240
	v_mfma_f32_16x16x32_bf16 v[124:127], v[218:221], v[226:229], v[124:127]
	s_waitcnt lgkmcnt(1)
; #define LAS __attribute__((address_space(3)))
; __device__ __forceinline__ unsigned pk2(float lo, float hi) { return pg8::cvt_pk_bf16(lo, hi); }
; __device__ __forceinline__ f32x4 mfma16(bf16x8 a, bf16x8 b, f32x4 c) { return __builtin_amdgcn_mfma_f32_16x16x32_bf16(a, b, c, 0, 0, 0); }
; #define LDS_FENCE() asm volatile("s_waitcnt lgkmcnt(0)" ::: "memory")
; template <bool DIAG, int NST>
; __device__ __forceinline__ void attn_tile(LAS unsigned char* lds, const bf16x8 (&qf)[4], f32x4 (&accO)[8], float& R, int w, int l15, int quad, int tl, bf16x8 U1, bf16x8 T0, bf16x8 T1) {
;     ...
;     { bf16x8 bb[4];
; #pragma unroll
;       for (int kj = 0; kj < NST / 2; ++kj) bb[kj] = *(const LAS bf16x8*)(lds + AT_P + tl * 272 + (32 * kj + 8 * quad) * 2);
;       rs += __shfl_xor(rs, 16); rs += __shfl_xor(rs, 32);
; #pragma unroll
;       for (int st = 0; st < NST; ++st) {
;           u32x2 wv = {0u, 0u};
;           if (true) {
;               f32x4 cs = (f32x4){0.f, 0.f, 0.f, 0.f};
; #pragma unroll
;               for (int kj = st >> 1; kj < NST / 2; ++kj) { const int dd = 2 * kj - st; cs = mfma16(dd == 0 ? T0 : (dd == -1 ? T1 : U1), bb[kj], cs); }
;               float a[4];
; #pragma unroll
;               for (int j = 0; j < 4; ++j) { float av = __builtin_amdgcn_exp2f(z[st][j] + cs[j] + R);
;                   if (DIAG) { const int s = 16 * st + 4 * quad + j; av = (s < tl) ? av : 0.f; }
;                   a[j] = av; }
;               wv.x = pk2(a[0], a[1]); wv.y = pk2(a[2], a[3]); }
;           *(LAS u32x2*)(lds + AT_P + tl * 272 + (16 * st + 4 * quad) * 2) = wv; } }
;     R += rs;
;     LDS_FENCE();
	v_mfma_f32_16x16x32_bf16 v[214:217], v[218:221], v[230:233], v[214:217]
	v_mfma_f32_16x16x32_bf16 v[124:127], v[218:221], v[230:233], v[124:127]
	s_nop 6
	v_add_f32_e32 v134, v152, v214
	v_add_f32_e32 v135, v149, v215
	v_add_f32_e32 v149, v150, v216
	v_add_f32_e32 v150, v151, v217
	v_add_f32_e32 v134, v165, v134
	v_add_f32_e32 v135, v165, v135
	v_add_f32_e32 v149, v165, v149
	v_add_f32_e32 v150, v165, v150
	v_add_f32_e32 v124, v144, v124
	v_exp_f32_e32 v134, v134
	v_exp_f32_e32 v135, v135
	v_exp_f32_e32 v149, v149
	v_exp_f32_e32 v150, v150
	v_add_f32_e32 v124, v165, v124
	v_exp_f32_e32 v124, v124
	v_cndmask_b32_e64 v134, 0, v134, s[8:9]
	v_cndmask_b32_e64 v135, 0, v135, s[10:11]
	v_cndmask_b32_e64 v149, 0, v149, s[12:13]
	v_cndmask_b32_e64 v144, 0, v150, s[14:15]
	v_cvt_pk_bf16_f32 v134, v134, v135
	v_cvt_pk_bf16_f32 v135, v149, v144
	v_cndmask_b32_e64 v144, 0, v124, s[16:17]
	v_add_f32_e32 v124, v145, v125
	v_add_f32_e32 v124, v165, v124
	v_exp_f32_e32 v145, v124
	v_add_f32_e32 v124, v146, v126
	v_add_f32_e32 v124, v165, v124
	v_exp_f32_e32 v146, v124
	v_add_f32_e32 v124, v147, v127
	v_add_f32_e32 v124, v165, v124
	v_exp_f32_e32 v147, v124
	v_mfma_f32_16x16x32_bf16 v[124:127], v[4:7], v[128:131], 0
	v_cndmask_b32_e64 v145, 0, v145, s[18:19]
	v_cndmask_b32_e64 v146, 0, v146, s[20:21]
	v_cndmask_b32_e64 v147, 0, v147, s[22:23]
	v_mfma_f32_16x16x32_bf16 v[124:127], v[218:221], v[226:229], v[124:127]
	v_cvt_pk_bf16_f32 v144, v144, v145
	v_cvt_pk_bf16_f32 v145, v146, v147
	ds_write2_b64 v148, v[134:135], v[144:145] offset1:4
	v_mfma_f32_16x16x32_bf16 v[124:127], v[218:221], v[230:233], v[124:127]
	v_mfma_f32_16x16x32_bf16 v[128:131], v[0:3], v[128:131], 0
	v_mfma_f32_16x16x32_bf16 v[128:131], v[218:221], v[226:229], v[128:131]
	s_nop 5
	v_add_f32_e32 v124, v140, v124
	v_add_f32_e32 v124, v165, v124
	v_exp_f32_e32 v124, v124
	v_add_f32_e32 v125, v141, v125
	v_add_f32_e32 v126, v142, v126
	v_add_f32_e32 v125, v165, v125
	v_add_f32_e32 v126, v165, v126
	v_exp_f32_e32 v125, v125
	v_exp_f32_e32 v126, v126
	v_cndmask_b32_e64 v134, 0, v124, s[24:25]
	v_add_f32_e32 v124, v143, v127
	v_add_f32_e32 v124, v165, v124
	v_cndmask_b32_e64 v135, 0, v125, s[26:27]
	v_cndmask_b32_e64 v140, 0, v126, s[28:29]
	v_exp_f32_e32 v141, v124
	v_mfma_f32_16x16x32_bf16 v[124:127], v[218:221], v[230:233], v[128:131]
	s_nop 2
	v_cvt_pk_bf16_f32 v128, v134, v135
	v_cndmask_b32_e64 v129, 0, v141, s[30:31]
	s_nop 2
	v_add_f32_e32 v124, v136, v124
	v_add_f32_e32 v124, v165, v124
	v_exp_f32_e32 v124, v124
	v_cvt_pk_bf16_f32 v129, v140, v129
	v_cndmask_b32_e64 v130, 0, v124, s[34:35]
	v_add_f32_e32 v124, v137, v125
	v_add_f32_e32 v124, v165, v124
	v_exp_f32_e32 v131, v124
	v_add_f32_e32 v124, v138, v126
	v_add_f32_e32 v124, v165, v124
	v_exp_f32_e32 v134, v124
	v_add_f32_e32 v124, v139, v127
	v_add_f32_e32 v124, v165, v124
	v_exp_f32_e32 v135, v124
	v_mfma_f32_16x16x32_bf16 v[124:127], v[4:7], v[226:229], 0
	v_cndmask_b32_e64 v131, 0, v131, s[36:37]
	v_cndmask_b32_e64 v134, 0, v134, s[38:39]
	v_cndmask_b32_e64 v135, 0, v135, s[40:41]
	v_mfma_f32_16x16x32_bf16 v[124:127], v[218:221], v[230:233], v[124:127]
	v_cvt_pk_bf16_f32 v130, v130, v131
	v_cvt_pk_bf16_f32 v131, v134, v135
	ds_write2_b64 v148, v[128:129], v[130:131] offset0:8 offset1:12
	s_nop 4
	v_add_f32_e32 v124, v132, v124
	v_add_f32_e32 v124, v165, v124
	v_exp_f32_e32 v124, v124
	s_nop 0
	v_cndmask_b32_e64 v128, 0, v124, s[42:43]
	v_add_f32_e32 v124, v133, v125
	v_add_f32_e32 v125, v154, v126
	v_add_f32_e32 v124, v165, v124
	v_add_f32_e32 v125, v165, v125
	v_exp_f32_e32 v124, v124
	v_exp_f32_e32 v125, v125
	v_add_f32_e32 v126, v222, v127
	v_add_f32_e32 v126, v165, v126
	v_exp_f32_e32 v129, v126
	v_cndmask_b32_e64 v130, 0, v124, s[44:45]
	v_cndmask_b32_e64 v131, 0, v125, s[46:47]
	v_mfma_f32_16x16x32_bf16 v[124:127], v[0:3], v[226:229], 0
	v_cndmask_b32_e64 v129, 0, v129, s[48:49]
	v_cvt_pk_bf16_f32 v128, v128, v130
	v_cvt_pk_bf16_f32 v129, v131, v129
	v_mfma_f32_16x16x32_bf16 v[124:127], v[218:221], v[230:233], v[124:127]
	v_xor_b32_e32 v130, 32, v206
	v_cmp_lt_i32_e32 vcc, v130, v244
	s_waitcnt lgkmcnt(2)
	v_add_f32_e32 v131, v243, v245
	v_cndmask_b32_e32 v130, v206, v130, vcc
	s_nop 2
	v_add_f32_e32 v124, v155, v124
	v_add_f32_e32 v125, v153, v125
	v_add_f32_e32 v126, v223, v126
	v_add_f32_e32 v127, v234, v127
	v_add_f32_e32 v124, v165, v124
	v_add_f32_e32 v125, v165, v125
	v_add_f32_e32 v126, v165, v126
	v_add_f32_e32 v127, v165, v127
	v_exp_f32_e32 v124, v124
	v_exp_f32_e32 v125, v125
	v_exp_f32_e32 v126, v126
	v_exp_f32_e32 v127, v127
	v_cndmask_b32_e64 v124, 0, v124, s[50:51]
	v_cndmask_b32_e64 v125, 0, v125, s[52:53]
	v_cndmask_b32_e64 v126, 0, v126, s[54:55]
	v_cndmask_b32_e64 v127, 0, v127, s[56:57]
	v_cvt_pk_bf16_f32 v124, v124, v125
	v_cvt_pk_bf16_f32 v125, v126, v127
	ds_write2_b64 v148, v[128:129], v[124:125] offset0:16 offset1:20
	v_mfma_f32_16x16x32_bf16 v[124:127], v[4:7], v[230:233], 0
	v_lshlrev_b32_e32 v130, 2, v130
	s_nop 6
	v_add_f32_e32 v124, v235, v124
	v_add_f32_e32 v125, v236, v125
	v_add_f32_e32 v126, v237, v126
	v_add_f32_e32 v127, v238, v127
	v_add_f32_e32 v124, v165, v124
	v_add_f32_e32 v125, v165, v125
	v_add_f32_e32 v126, v165, v126
	v_add_f32_e32 v127, v165, v127
	v_exp_f32_e32 v124, v124
	v_exp_f32_e32 v125, v125
	v_exp_f32_e32 v126, v126
	v_exp_f32_e32 v127, v127
	v_cndmask_b32_e64 v124, 0, v124, s[58:59]
	v_cndmask_b32_e64 v125, 0, v125, s[60:61]
	v_cndmask_b32_e64 v126, 0, v126, s[62:63]
	v_cndmask_b32_e64 v127, 0, v127, s[64:65]
	v_cvt_pk_bf16_f32 v128, v124, v125
	v_cvt_pk_bf16_f32 v129, v126, v127
	v_mfma_f32_16x16x32_bf16 v[124:127], v[0:3], v[230:233], 0
	s_nop 7
	v_add_f32_e32 v120, v120, v124
	v_add_f32_e32 v121, v121, v125
	v_add_f32_e32 v122, v122, v126
	v_add_f32_e32 v123, v123, v127
	v_add_f32_e32 v120, v165, v120
	v_add_f32_e32 v121, v165, v121
	v_add_f32_e32 v122, v165, v122
	v_add_f32_e32 v123, v165, v123
	v_exp_f32_e32 v120, v120
	v_exp_f32_e32 v121, v121
	v_exp_f32_e32 v122, v122
	v_exp_f32_e32 v123, v123
	v_cndmask_b32_e64 v120, 0, v120, s[66:67]
	v_cndmask_b32_e64 v121, 0, v121, s[68:69]
	v_cndmask_b32_e64 v122, 0, v122, s[70:71]
	v_cndmask_b32_e64 v123, 0, v123, s[72:73]
	ds_bpermute_b32 v124, v130, v131
	v_cvt_pk_bf16_f32 v120, v120, v121
	v_cvt_pk_bf16_f32 v121, v122, v123
	ds_write2_b64 v148, v[128:129], v[120:121] offset0:24 offset1:28
	s_waitcnt lgkmcnt(0)
	s_waitcnt lgkmcnt(1)
	v_add_f32_e32 v214, v131, v124
	s_cbranch_execz .LBB0_997
	s_branch .LBB0_998

; #define LAS __attribute__((address_space(3)))
; __device__ __forceinline__ unsigned pk2(float lo, float hi) { return pg8::cvt_pk_bf16(lo, hi); }
; __device__ __forceinline__ f32x4 mfma16(bf16x8 a, bf16x8 b, f32x4 c) { return __builtin_amdgcn_mfma_f32_16x16x32_bf16(a, b, c, 0, 0, 0); }
; template <bool DIAG, int NST>
; __device__ __forceinline__ void attn_tile(LAS unsigned char* lds, const bf16x8 (&qf)[4], f32x4 (&accO)[8], float& R, int w, int l15, int quad, int tl, bf16x8 U1, bf16x8 T0, bf16x8 T1) {
;     ...
;     f32x4 z[8];
; #pragma unroll
;     for (int st = 0; st < NST; ++st) { z[st] = (f32x4){0.f, 0.f, 0.f, 0.f};
;         if (true) {
; #pragma unroll
;             for (int ks = 0; ks < 4; ++ks) { const bf16x8 a = *(const LAS bf16x8*)(lds + AT_KS + (16 * st + l15) * 272 + (32 * ks + 8 * quad) * 2); z[st] = mfma16(a, qf[ks], z[st]); } }
;         if (st & 1) __builtin_amdgcn_sched_barrier(0); }
;     float rs = 0.f;
; #pragma unroll
;     for (int st = 0; st < NST; ++st) {
;         u32x2 wv = {0u, 0u};
;         if (true) { float lk[4];
; #pragma unroll
;             for (int j = 0; j < 4; ++j) { const float z2 = z[st][j] * SCALE2; float sp = __builtin_amdgcn_logf(1.0f + __builtin_amdgcn_exp2f(z2)); sp = (z2 > 64.0f) ? z2 : sp;
;                 if (DIAG) { const int s = 16 * st + 4 * quad + j; lk[j] = (s < tl) ? -sp : 0.f; } else lk[j] = -sp;
;                 z[st][j] = z2 - sp; rs += lk[j]; }
;             wv.x = pk2(lk[0], lk[1]); wv.y = pk2(lk[2], lk[3]); }
;         *(LAS u32x2*)(lds + AT_P + tl * 272 + (16 * st + 4 * quad) * 2) = wv;
;         if (st & 1) __builtin_amdgcn_sched_barrier(0); }
.LBB0_997:
	s_waitcnt lgkmcnt(7)
	v_mfma_f32_16x16x32_bf16 v[120:123], v[88:91], v[24:27], 0
	s_waitcnt lgkmcnt(6)
	v_mfma_f32_16x16x32_bf16 v[92:95], v[92:95], v[28:31], v[120:123]
	s_waitcnt lgkmcnt(5)
	v_mfma_f32_16x16x32_bf16 v[92:95], v[96:99], v[32:35], v[92:95]
	s_waitcnt lgkmcnt(4)
	v_mfma_f32_16x16x32_bf16 v[120:123], v[100:103], v[36:39], v[92:95]
	s_waitcnt lgkmcnt(3)
	v_mfma_f32_16x16x32_bf16 v[92:95], v[104:107], v[24:27], 0
	s_waitcnt lgkmcnt(2)
	v_mfma_f32_16x16x32_bf16 v[92:95], v[108:111], v[28:31], v[92:95]
	s_waitcnt lgkmcnt(1)
	v_mfma_f32_16x16x32_bf16 v[92:95], v[112:115], v[32:35], v[92:95]
	s_waitcnt lgkmcnt(0)
	v_mfma_f32_16x16x32_bf16 v[100:103], v[116:119], v[36:39], v[92:95]
	s_nop 5
	ds_read_b128 v[92:95], v173 offset:8704
	ds_read_b128 v[96:99], v173 offset:8768
	s_waitcnt lgkmcnt(1)
	v_mfma_f32_16x16x32_bf16 v[92:95], v[92:95], v[24:27], 0
	ds_read_b128 v[104:107], v173 offset:13120
	s_waitcnt lgkmcnt(1)
	v_mfma_f32_16x16x32_bf16 v[92:95], v[96:99], v[28:31], v[92:95]
	ds_read_b128 v[96:99], v173 offset:8832
	s_waitcnt lgkmcnt(0)
	v_mfma_f32_16x16x32_bf16 v[92:95], v[96:99], v[32:35], v[92:95]
	ds_read_b128 v[96:99], v173 offset:8896
	s_waitcnt lgkmcnt(0)
	v_mfma_f32_16x16x32_bf16 v[96:99], v[96:99], v[36:39], v[92:95]
	s_nop 4
	ds_read_b128 v[92:95], v173 offset:13056
	s_waitcnt lgkmcnt(0)
	v_mfma_f32_16x16x32_bf16 v[92:95], v[92:95], v[24:27], 0
	v_mfma_f32_16x16x32_bf16 v[92:95], v[104:107], v[28:31], v[92:95]
	ds_read_b128 v[104:107], v173 offset:13184
	s_waitcnt lgkmcnt(0)
	v_mfma_f32_16x16x32_bf16 v[92:95], v[104:107], v[32:35], v[92:95]
	ds_read_b128 v[104:107], v173 offset:13248
	s_waitcnt lgkmcnt(0)
	v_mfma_f32_16x16x32_bf16 v[92:95], v[104:107], v[36:39], v[92:95]
	v_mul_f32_e32 v104, 0x3e0293ee, v120
	v_exp_f32_e32 v105, v104
	v_cmp_lt_f32_e32 vcc, s5, v104
	v_add_u32_e32 v116, v174, v158
	v_add_f32_e32 v105, 1.0, v105
	v_log_f32_e32 v105, v105
	s_nop 0
	v_cndmask_b32_e32 v104, v105, v104, vcc
	v_cndmask_b32_e64 v106, 0, -v104, s[8:9]
	v_fma_f32 v112, v120, s88, -v104
	v_mul_f32_e32 v104, 0x3e0293ee, v121
	v_exp_f32_e32 v105, v104
	v_cmp_lt_f32_e32 vcc, s5, v104
	v_add_f32_e32 v105, 1.0, v105
	v_log_f32_e32 v105, v105
	s_nop 0
	v_cndmask_b32_e32 v104, v105, v104, vcc
	v_cndmask_b32_e64 v107, 0, -v104, s[10:11]
	v_fma_f32 v113, v121, s88, -v104
	v_mul_f32_e32 v104, 0x3e0293ee, v122
	v_exp_f32_e32 v105, v104
	v_cmp_lt_f32_e32 vcc, s5, v104
	v_add_f32_e32 v105, 1.0, v105
	v_log_f32_e32 v105, v105
	s_nop 0
	v_cndmask_b32_e32 v104, v105, v104, vcc
	v_cndmask_b32_e64 v108, 0, -v104, s[12:13]
	v_fma_f32 v114, v122, s88, -v104
	v_mul_f32_e32 v104, 0x3e0293ee, v123
	v_exp_f32_e32 v105, v104
	v_cmp_lt_f32_e32 vcc, s5, v104
	v_add_f32_e32 v105, 1.0, v105
	v_log_f32_e32 v105, v105
	s_nop 0
	v_cndmask_b32_e32 v104, v105, v104, vcc
	v_cndmask_b32_e64 v109, 0, -v104, s[14:15]
	v_fma_f32 v115, v123, s88, -v104
	v_cvt_pk_bf16_f32 v104, v106, v107
	v_add_f32_e32 v106, 0, v106
	v_add_f32_e32 v106, v107, v106
	v_mul_f32_e32 v107, 0x3e0293ee, v100
	v_cvt_pk_bf16_f32 v105, v108, v109
	v_add_f32_e32 v106, v108, v106
	v_exp_f32_e32 v108, v107
	v_cmp_lt_f32_e32 vcc, s5, v107
	v_add_f32_e32 v106, v109, v106
	v_add_f32_e32 v108, 1.0, v108
	v_log_f32_e32 v108, v108
	s_nop 0
	v_cndmask_b32_e32 v107, v108, v107, vcc
	v_cndmask_b32_e64 v108, 0, -v107, s[16:17]
	v_fma_f32 v117, v100, s88, -v107
	v_add_f32_e32 v100, v106, v108
	v_mul_f32_e32 v106, 0x3e0293ee, v101
	v_exp_f32_e32 v107, v106
	v_cmp_lt_f32_e32 vcc, s5, v106
	v_add_f32_e32 v107, 1.0, v107
	v_log_f32_e32 v107, v107
	s_nop 0
	v_cndmask_b32_e32 v106, v107, v106, vcc
	v_fma_f32 v118, v101, s88, -v106
	v_mul_f32_e32 v101, 0x3e0293ee, v102
	v_cndmask_b32_e64 v107, 0, -v106, s[18:19]
	v_exp_f32_e32 v106, v101
	v_cmp_lt_f32_e32 vcc, s5, v101
	v_add_f32_e32 v100, v107, v100
	v_add_f32_e32 v106, 1.0, v106
	v_log_f32_e32 v106, v106
	s_nop 0
	v_cndmask_b32_e32 v101, v106, v101, vcc
	v_cndmask_b32_e64 v106, 0, -v101, s[20:21]
	v_fma_f32 v119, v102, s88, -v101
	v_mul_f32_e32 v101, 0x3e0293ee, v103
	v_exp_f32_e32 v102, v101
	v_cmp_lt_f32_e32 vcc, s5, v101
	v_add_f32_e32 v100, v106, v100
	v_add_f32_e32 v102, 1.0, v102
	v_log_f32_e32 v102, v102
	s_nop 0
	v_cndmask_b32_e32 v101, v102, v101, vcc
	v_cndmask_b32_e64 v102, 0, -v101, s[22:23]
	v_fma_f32 v120, v103, s88, -v101
	v_add_f32_e32 v103, v102, v100
	v_cvt_pk_bf16_f32 v100, v108, v107
	v_cvt_pk_bf16_f32 v101, v106, v102
	ds_write2_b64 v116, v[104:105], v[100:101] offset1:4
	v_mul_f32_e32 v100, 0x3e0293ee, v96
	v_exp_f32_e32 v101, v100
	v_mul_f32_e32 v102, 0x3e0293ee, v97
	v_exp_f32_e32 v104, v102
	v_cmp_lt_f32_e32 vcc, s5, v100
	v_add_f32_e32 v101, 1.0, v101
	v_log_f32_e32 v101, v101
	v_add_f32_e32 v104, 1.0, v104
	v_log_f32_e32 v104, v104
	v_mul_f32_e32 v105, 0x3e0293ee, v99
	v_cndmask_b32_e32 v100, v101, v100, vcc
	v_fma_f32 v121, v96, s88, -v100
	v_mul_f32_e32 v96, 0x3e0293ee, v98
	v_cndmask_b32_e64 v101, 0, -v100, s[24:25]
	v_exp_f32_e32 v100, v96
	v_exp_f32_e32 v106, v105
	v_cmp_lt_f32_e32 vcc, s5, v102
	v_add_f32_e32 v100, 1.0, v100
	s_nop 0
	v_cndmask_b32_e32 v102, v104, v102, vcc
	v_log_f32_e32 v100, v100
	v_fma_f32 v122, v97, s88, -v102
	v_add_f32_e32 v97, 1.0, v106
	v_log_f32_e32 v97, v97
	v_cmp_lt_f32_e32 vcc, s5, v96
	v_cndmask_b32_e64 v104, 0, -v102, s[26:27]
	s_nop 0
	v_cndmask_b32_e32 v96, v100, v96, vcc
	v_cmp_lt_f32_e32 vcc, s5, v105
	v_cndmask_b32_e64 v100, 0, -v96, s[28:29]
	v_fma_f32 v123, v98, s88, -v96
	v_cndmask_b32_e32 v96, v97, v105, vcc
	v_cndmask_b32_e64 v98, 0, -v96, s[30:31]
	v_fma_f32 v124, v99, s88, -v96
	v_cvt_pk_bf16_f32 v96, v101, v104
	v_add_f32_e32 v99, v103, v101
	v_mul_f32_e32 v101, 0x3e0293ee, v92
	v_exp_f32_e32 v102, v101
	v_add_f32_e32 v99, v104, v99
	v_add_f32_e32 v99, v100, v99
	v_cvt_pk_bf16_f32 v97, v100, v98
	v_add_f32_e32 v98, v98, v99
	v_add_f32_e32 v99, 1.0, v102
	v_mul_f32_e32 v100, 0x3e0293ee, v93
	v_log_f32_e32 v99, v99
	v_exp_f32_e32 v102, v100
	v_cmp_lt_f32_e32 vcc, s5, v101
	s_nop 1
	v_cndmask_b32_e32 v125, v99, v101, vcc
	v_add_f32_e32 v101, 1.0, v102
	v_mul_f32_e32 v102, 0x3e0293ee, v94
	v_log_f32_e32 v101, v101
	v_exp_f32_e32 v103, v102
	v_cmp_lt_f32_e32 vcc, s5, v100
	v_cndmask_b32_e64 v99, 0, -v125, s[34:35]
	v_add_f32_e32 v98, v98, v99
	v_cndmask_b32_e32 v126, v101, v100, vcc
	v_add_f32_e32 v101, 1.0, v103
	v_mul_f32_e32 v103, 0x3e0293ee, v95
	v_log_f32_e32 v101, v101
	v_exp_f32_e32 v104, v103
	v_cmp_lt_f32_e32 vcc, s5, v102
	v_cndmask_b32_e64 v100, 0, -v126, s[36:37]
	v_add_f32_e32 v98, v100, v98
	v_cndmask_b32_e32 v127, v101, v102, vcc
	v_add_f32_e32 v101, 1.0, v104
	v_log_f32_e32 v101, v101
	v_cmp_lt_f32_e32 vcc, s5, v103
	v_cndmask_b32_e64 v102, 0, -v127, s[38:39]
	v_add_f32_e32 v98, v102, v98
	v_cndmask_b32_e32 v128, v101, v103, vcc
	v_cndmask_b32_e64 v101, 0, -v128, s[40:41]
	v_add_f32_e32 v129, v101, v98
	v_cvt_pk_bf16_f32 v98, v99, v100
	v_cvt_pk_bf16_f32 v99, v102, v101
	ds_write2_b64 v116, v[96:97], v[98:99] offset0:8 offset1:12
	s_waitcnt lgkmcnt(0)
; #define LAS __attribute__((address_space(3)))
; __device__ __forceinline__ unsigned pk2(float lo, float hi) { return pg8::cvt_pk_bf16(lo, hi); }
; __device__ __forceinline__ f32x4 mfma16(bf16x8 a, bf16x8 b, f32x4 c) { return __builtin_amdgcn_mfma_f32_16x16x32_bf16(a, b, c, 0, 0, 0); }
; #define LDS_FENCE() asm volatile("s_waitcnt lgkmcnt(0)" ::: "memory")
; template <bool DIAG, int NST>
; __device__ __forceinline__ void attn_tile(LAS unsigned char* lds, const bf16x8 (&qf)[4], f32x4 (&accO)[8], float& R, int w, int l15, int quad, int tl, bf16x8 U1, bf16x8 T0, bf16x8 T1) {
;     ...
;     { bf16x8 bb[4];
; #pragma unroll
;       for (int kj = 0; kj < NST / 2; ++kj) bb[kj] = *(const LAS bf16x8*)(lds + AT_P + tl * 272 + (32 * kj + 8 * quad) * 2);
;       rs += __shfl_xor(rs, 16); rs += __shfl_xor(rs, 32);
; #pragma unroll
;       for (int st = 0; st < NST; ++st) {
;           u32x2 wv = {0u, 0u};
;           if (true) {
;               f32x4 cs = (f32x4){0.f, 0.f, 0.f, 0.f};
; #pragma unroll
;               for (int kj = st >> 1; kj < NST / 2; ++kj) { const int dd = 2 * kj - st; cs = mfma16(dd == 0 ? T0 : (dd == -1 ? T1 : U1), bb[kj], cs); }
;               float a[4];
; #pragma unroll
;               for (int j = 0; j < 4; ++j) { float av = __builtin_amdgcn_exp2f(z[st][j] + cs[j] + R);
;                   if (DIAG) { const int s = 16 * st + 4 * quad + j; av = (s < tl) ? av : 0.f; }
;                   a[j] = av; }
;               wv.x = pk2(a[0], a[1]); wv.y = pk2(a[2], a[3]); }
;           *(LAS u32x2*)(lds + AT_P + tl * 272 + (16 * st + 4 * quad) * 2) = wv; } }
;     R += rs;
;     LDS_FENCE();
	ds_read_b128 v[96:99], v167
	ds_read_b128 v[100:103], v167 offset:64
	s_mov_b32 s78, s76
	s_mov_b32 s79, s76
	s_mov_b32 s77, s76
	v_mov_b64_e32 v[106:107], s[78:79]
	v_mov_b64_e32 v[104:105], s[76:77]
	s_waitcnt lgkmcnt(1)
	v_mfma_f32_16x16x32_bf16 v[108:111], v[4:7], v[96:99], 0
	v_and_b32_e32 v131, 64, v206
	v_xor_b32_e32 v130, 16, v206
	v_add_u32_e32 v131, 64, v131
	v_mfma_f32_16x16x32_bf16 v[96:99], v[0:3], v[96:99], 0
	v_cmp_lt_i32_e32 vcc, v130, v131
	v_fma_f32 v92, v92, s88, -v125
	v_fma_f32 v95, v95, s88, -v128
	s_waitcnt lgkmcnt(0)
	v_mfma_f32_16x16x32_bf16 v[108:111], v[104:107], v[100:103], v[108:111]
	v_cndmask_b32_e32 v130, v206, v130, vcc
	v_fma_f32 v94, v94, s88, -v127
	v_fma_f32 v93, v93, s88, -v126
	v_mfma_f32_16x16x32_bf16 v[96:99], v[104:107], v[100:103], v[96:99]
	s_nop 3
	v_add_f32_e32 v108, v112, v108
	v_add_f32_e32 v109, v113, v109
	v_add_f32_e32 v110, v114, v110
	v_add_f32_e32 v111, v115, v111
	v_add_f32_e32 v96, v117, v96
	v_add_f32_e32 v97, v118, v97
	v_add_f32_e32 v98, v119, v98
	v_add_f32_e32 v99, v120, v99
	v_add_f32_e32 v108, v165, v108
	v_add_f32_e32 v109, v165, v109
	v_add_f32_e32 v110, v165, v110
	v_add_f32_e32 v111, v165, v111
	v_add_f32_e32 v96, v165, v96
	v_add_f32_e32 v97, v165, v97
	v_add_f32_e32 v98, v165, v98
	v_add_f32_e32 v99, v165, v99
	v_exp_f32_e32 v108, v108
	v_exp_f32_e32 v109, v109
	v_exp_f32_e32 v110, v110
	v_exp_f32_e32 v111, v111
	v_exp_f32_e32 v96, v96
	v_exp_f32_e32 v97, v97
	v_exp_f32_e32 v98, v98
	v_exp_f32_e32 v99, v99
	v_cndmask_b32_e64 v108, 0, v108, s[8:9]
	v_cndmask_b32_e64 v109, 0, v109, s[10:11]
	v_cndmask_b32_e64 v110, 0, v110, s[12:13]
	v_cndmask_b32_e64 v111, 0, v111, s[14:15]
	v_cndmask_b32_e64 v96, 0, v96, s[16:17]
	v_cndmask_b32_e64 v97, 0, v97, s[18:19]
	v_cndmask_b32_e64 v98, 0, v98, s[20:21]
	v_cndmask_b32_e64 v99, 0, v99, s[22:23]
	v_cvt_pk_bf16_f32 v108, v108, v109
	v_cvt_pk_bf16_f32 v109, v110, v111
	v_cvt_pk_bf16_f32 v96, v96, v97
	v_cvt_pk_bf16_f32 v97, v98, v99
	ds_write2_b64 v116, v[108:109], v[96:97] offset1:4
	v_mfma_f32_16x16x32_bf16 v[96:99], v[4:7], v[100:103], 0
	v_lshlrev_b32_e32 v112, 2, v130
	ds_bpermute_b32 v112, v112, v129
	s_nop 5
	v_add_f32_e32 v96, v121, v96
	v_add_f32_e32 v97, v122, v97
	v_add_f32_e32 v98, v123, v98
	v_add_f32_e32 v99, v124, v99
	v_add_f32_e32 v96, v165, v96
	v_add_f32_e32 v97, v165, v97
	v_add_f32_e32 v98, v165, v98
	v_add_f32_e32 v99, v165, v99
	v_exp_f32_e32 v96, v96
	v_exp_f32_e32 v97, v97
	v_exp_f32_e32 v98, v98
	v_exp_f32_e32 v99, v99
	v_cndmask_b32_e64 v96, 0, v96, s[24:25]
	v_cndmask_b32_e64 v97, 0, v97, s[26:27]
	v_cndmask_b32_e64 v98, 0, v98, s[28:29]
	v_cndmask_b32_e64 v99, 0, v99, s[30:31]
	v_cvt_pk_bf16_f32 v104, v96, v97
	v_cvt_pk_bf16_f32 v105, v98, v99
	v_mfma_f32_16x16x32_bf16 v[96:99], v[0:3], v[100:103], 0
	v_xor_b32_e32 v100, 32, v206
	v_cmp_lt_i32_e32 vcc, v100, v131
	s_waitcnt lgkmcnt(0)
	v_add_f32_e32 v101, v129, v112
	v_cndmask_b32_e32 v100, v206, v100, vcc
	s_nop 2
	v_add_f32_e32 v92, v92, v96
	v_add_f32_e32 v93, v93, v97
	v_add_f32_e32 v94, v94, v98
	v_add_f32_e32 v95, v95, v99
	v_add_f32_e32 v92, v165, v92
	v_add_f32_e32 v93, v165, v93
	v_add_f32_e32 v94, v165, v94
	v_add_f32_e32 v95, v165, v95
	v_exp_f32_e32 v92, v92
	v_exp_f32_e32 v93, v93
	v_exp_f32_e32 v94, v94
	v_exp_f32_e32 v95, v95
	v_lshlrev_b32_e32 v100, 2, v100
	v_cndmask_b32_e64 v92, 0, v92, s[34:35]
	v_cndmask_b32_e64 v93, 0, v93, s[36:37]
	v_cndmask_b32_e64 v94, 0, v94, s[38:39]
	ds_bpermute_b32 v96, v100, v101
	v_cndmask_b32_e64 v95, 0, v95, s[40:41]
	v_cvt_pk_bf16_f32 v92, v92, v93
	v_cvt_pk_bf16_f32 v93, v94, v95
	ds_write2_b64 v116, v[104:105], v[92:93] offset0:8 offset1:12
	s_waitcnt lgkmcnt(0)
	s_waitcnt lgkmcnt(1)
	v_add_f32_e32 v214, v101, v96

; template <bool DIAG, int NST>
; __device__ __forceinline__ void attn_tile(LAS unsigned char* lds, const bf16x8 (&qf)[4], f32x4 (&accO)[8], float& R, int w, int l15, int quad, int tl, bf16x8 U1, bf16x8 T0, bf16x8 T1) {
;     ...
;     f32x4 z[8];
; #pragma unroll
;     for (int st = 0; st < NST; ++st) { z[st] = (f32x4){0.f, 0.f, 0.f, 0.f};
;         if (true) {
; #pragma unroll
;             for (int ks = 0; ks < 4; ++ks) { const bf16x8 a = *(const LAS bf16x8*)(lds + AT_KS + (16 * st + l15) * 272 + (32 * ks + 8 * quad) * 2); z[st] = mfma16(a, qf[ks], z[st]); } }
;         if (st & 1) __builtin_amdgcn_sched_barrier(0); }
;     float rs = 0.f;
; #pragma unroll
;     for (int st = 0; st < NST; ++st) {
;         u32x2 wv = {0u, 0u};
;         if (true) { float lk[4];
; #pragma unroll
;             for (int j = 0; j < 4; ++j) { const float z2 = z[st][j] * SCALE2; float sp = __builtin_amdgcn_logf(1.0f + __builtin_amdgcn_exp2f(z2)); sp = (z2 > 64.0f) ? z2 : sp;
;                 if (DIAG) { const int s = 16 * st + 4 * quad + j; lk[j] = (s < tl) ? -sp : 0.f; } else lk[j] = -sp;
;                 z[st][j] = z2 - sp; rs += lk[j]; }
;             wv.x = pk2(lk[0], lk[1]); wv.y = pk2(lk[2], lk[3]); }
;         *(LAS u32x2*)(lds + AT_P + tl * 272 + (16 * st + 4 * quad) * 2) = wv;
;         if (st & 1) __builtin_amdgcn_sched_barrier(0); }
;     LDS_FENCE();
;     { bf16x8 bb[4];
; #pragma unroll
;       for (int kj = 0; kj < NST / 2; ++kj) bb[kj] = *(const LAS bf16x8*)(lds + AT_P + tl * 272 + (32 * kj + 8 * quad) * 2);
;       rs += __shfl_xor(rs, 16); rs += __shfl_xor(rs, 32);
; #pragma unroll
;       for (int st = 0; st < NST; ++st) {
;           u32x2 wv = {0u, 0u};
;           if (true) {
;               f32x4 cs = (f32x4){0.f, 0.f, 0.f, 0.f};
; #pragma unroll
;               for (int kj = st >> 1; kj < NST / 2; ++kj) { const int dd = 2 * kj - st; cs = mfma16(dd == 0 ? T0 : (dd == -1 ? T1 : U1), bb[kj], cs); }
;               float a[4];
; #pragma unroll
;               for (int j = 0; j < 4; ++j) { float av = __builtin_amdgcn_exp2f(z[st][j] + cs[j] + R);
;                   if (DIAG) { const int s = 16 * st + 4 * quad + j; av = (s < tl) ? av : 0.f; }
;                   a[j] = av; }
;               wv.x = pk2(a[0], a[1]); wv.y = pk2(a[2], a[3]); }
;           *(LAS u32x2*)(lds + AT_P + tl * 272 + (16 * st + 4 * quad) * 2) = wv; } }
;     R += rs;
;     LDS_FENCE();
.LBB0_999:
	s_and_b64 vcc, exec, s[78:79]
	s_cbranch_vccz .LBB0_1001
	s_waitcnt lgkmcnt(6)
	ds_read_b128 v[92:95], v173 offset:64
	s_waitcnt lgkmcnt(6)
	ds_read_b128 v[96:99], v173 offset:4416
	s_waitcnt lgkmcnt(2)
	v_mfma_f32_16x16x32_bf16 v[88:91], v[88:91], v[24:27], 0
	s_waitcnt lgkmcnt(1)
	v_mfma_f32_16x16x32_bf16 v[88:91], v[92:95], v[28:31], v[88:91]
	ds_read_b128 v[92:95], v173 offset:128
	s_waitcnt lgkmcnt(0)
	v_mfma_f32_16x16x32_bf16 v[88:91], v[92:95], v[32:35], v[88:91]
	ds_read_b128 v[92:95], v173 offset:192
	s_waitcnt lgkmcnt(0)
	v_mfma_f32_16x16x32_bf16 v[88:91], v[92:95], v[36:39], v[88:91]
	ds_read_b128 v[92:95], v173 offset:4352
	s_waitcnt lgkmcnt(0)
	v_mfma_f32_16x16x32_bf16 v[92:95], v[92:95], v[24:27], 0
	v_mfma_f32_16x16x32_bf16 v[92:95], v[96:99], v[28:31], v[92:95]
	ds_read_b128 v[96:99], v173 offset:4480
	s_waitcnt lgkmcnt(0)
	v_mfma_f32_16x16x32_bf16 v[92:95], v[96:99], v[32:35], v[92:95]
	ds_read_b128 v[96:99], v173 offset:4544
	s_waitcnt lgkmcnt(0)
	v_mfma_f32_16x16x32_bf16 v[92:95], v[96:99], v[36:39], v[92:95]
	v_mul_f32_e32 v96, 0x3e0293ee, v88
	v_exp_f32_e32 v97, v96
	v_mul_f32_e32 v98, 0x3e0293ee, v89
	v_exp_f32_e32 v99, v98
	v_cmp_lt_f32_e32 vcc, s5, v96
	v_add_f32_e32 v97, 1.0, v97
	v_log_f32_e32 v97, v97
	v_add_f32_e32 v99, 1.0, v99
	v_log_f32_e32 v99, v99
	v_mul_f32_e32 v108, 0x3e0293ee, v93
	v_cndmask_b32_e32 v100, v97, v96, vcc
	v_cmp_lt_f32_e32 vcc, s5, v98
	v_mul_f32_e32 v96, 0x3e0293ee, v90
	v_exp_f32_e32 v97, v96
	v_cndmask_b32_e32 v102, v99, v98, vcc
	v_mul_f32_e32 v98, 0x3e0293ee, v91
	v_exp_f32_e32 v99, v98
	v_add_f32_e32 v97, 1.0, v97
	v_log_f32_e32 v97, v97
	v_cmp_lt_f32_e32 vcc, s5, v96
	v_add_f32_e32 v99, 1.0, v99
	v_log_f32_e32 v99, v99
	v_cndmask_b32_e32 v104, v97, v96, vcc
	v_cmp_lt_f32_e32 vcc, s5, v98
	v_exp_f32_e32 v109, v108
	v_cndmask_b32_e64 v101, 0, -v100, s[8:9]
	v_cndmask_b32_e32 v106, v99, v98, vcc
	v_mul_f32_e32 v98, 0x3e0293ee, v92
	v_exp_f32_e32 v99, v98
	v_add_f32_e32 v109, 1.0, v109
	v_log_f32_e32 v109, v109
	v_cmp_lt_f32_e32 vcc, s5, v98
	v_add_f32_e32 v99, 1.0, v99
	v_log_f32_e32 v99, v99
	v_cndmask_b32_e64 v103, 0, -v102, s[10:11]
	v_cndmask_b32_e64 v105, 0, -v104, s[12:13]
	v_cndmask_b32_e64 v107, 0, -v106, s[14:15]
	v_cndmask_b32_e32 v111, v99, v98, vcc
	v_cmp_lt_f32_e32 vcc, s5, v108
	v_mul_f32_e32 v98, 0x3e0293ee, v94
	v_exp_f32_e32 v99, v98
	v_cndmask_b32_e32 v108, v109, v108, vcc
	v_mul_f32_e32 v109, 0x3e0293ee, v95
	v_exp_f32_e32 v113, v109
	v_add_f32_e32 v99, 1.0, v99
	v_log_f32_e32 v99, v99
	v_cmp_lt_f32_e32 vcc, s5, v98
	v_add_f32_e32 v113, 1.0, v113
	v_log_f32_e32 v113, v113
	v_cndmask_b32_e32 v115, v99, v98, vcc
	v_cmp_lt_f32_e32 vcc, s5, v109
	v_cndmask_b32_e64 v112, 0, -v111, s[16:17]
	v_cndmask_b32_e64 v114, 0, -v108, s[18:19]
	v_cndmask_b32_e32 v109, v113, v109, vcc
	v_cndmask_b32_e64 v116, 0, -v115, s[20:21]
	v_cndmask_b32_e64 v113, 0, -v109, s[22:23]
	v_cvt_pk_bf16_f32 v96, v101, v103
	v_cvt_pk_bf16_f32 v97, v105, v107
	v_add_u32_e32 v110, v174, v158
	v_cvt_pk_bf16_f32 v98, v112, v114
	v_cvt_pk_bf16_f32 v99, v116, v113
	ds_write2_b64 v110, v[96:97], v[98:99] offset1:4
	v_add_f32_e32 v96, 0, v101
	v_add_f32_e32 v96, v103, v96
	v_add_f32_e32 v96, v105, v96
	v_add_f32_e32 v96, v107, v96
	v_fma_f32 v103, v91, s88, -v106
	v_and_b32_e32 v91, 64, v206
	v_add_f32_e32 v96, v96, v112
	v_fma_f32 v101, v92, s88, -v111
	v_fma_f32 v104, v90, s88, -v104
	v_xor_b32_e32 v90, 16, v206
	v_add_u32_e32 v92, 64, v91
	v_add_f32_e32 v96, v114, v96
	v_cmp_lt_i32_e32 vcc, v90, v92
	v_add_f32_e32 v96, v116, v96
	v_add_f32_e32 v96, v113, v96
	v_cndmask_b32_e32 v90, v206, v90, vcc
	v_lshlrev_b32_e32 v90, 2, v90
	v_fma_f32 v99, v93, s88, -v108
	ds_bpermute_b32 v93, v90, v96
	s_waitcnt lgkmcnt(0)
	v_fma_f32 v102, v89, s88, -v102
	v_fma_f32 v100, v88, s88, -v100
	ds_read_b128 v[88:91], v167
	s_waitcnt lgkmcnt(1)
	v_add_f32_e32 v96, v96, v93
	v_xor_b32_e32 v93, 32, v206
	v_cmp_lt_i32_e32 vcc, v93, v92
	v_fma_f32 v97, v95, s88, -v109
	v_fma_f32 v98, v94, s88, -v115
	v_cndmask_b32_e32 v105, v206, v93, vcc
	s_waitcnt lgkmcnt(0)
	v_mfma_f32_16x16x32_bf16 v[92:95], v[4:7], v[88:91], 0
	v_mfma_f32_16x16x32_bf16 v[88:91], v[0:3], v[88:91], 0
	s_nop 6
	v_add_f32_e32 v92, v100, v92
	v_add_f32_e32 v93, v102, v93
	v_add_f32_e32 v94, v104, v94
	v_add_f32_e32 v95, v103, v95
	v_add_f32_e32 v92, v165, v92
	v_add_f32_e32 v93, v165, v93
	v_add_f32_e32 v94, v165, v94
	v_add_f32_e32 v95, v165, v95
	v_add_f32_e32 v88, v101, v88
	v_add_f32_e32 v89, v99, v89
	v_add_f32_e32 v90, v98, v90
	v_add_f32_e32 v91, v97, v91
	v_exp_f32_e32 v92, v92
	v_exp_f32_e32 v93, v93
	v_exp_f32_e32 v94, v94
	v_exp_f32_e32 v95, v95
	v_add_f32_e32 v88, v165, v88
	v_add_f32_e32 v89, v165, v89
	v_add_f32_e32 v90, v165, v90
	v_add_f32_e32 v91, v165, v91
	v_exp_f32_e32 v88, v88
	v_exp_f32_e32 v89, v89
	v_exp_f32_e32 v90, v90
	v_exp_f32_e32 v91, v91
	v_lshlrev_b32_e32 v100, 2, v105
	v_cndmask_b32_e64 v92, 0, v92, s[8:9]
	v_cndmask_b32_e64 v93, 0, v93, s[10:11]
	v_cndmask_b32_e64 v94, 0, v94, s[12:13]
	v_cndmask_b32_e64 v95, 0, v95, s[14:15]
	v_cvt_pk_bf16_f32 v92, v92, v93
	v_cvt_pk_bf16_f32 v93, v94, v95
	v_cndmask_b32_e64 v88, 0, v88, s[16:17]
	v_cndmask_b32_e64 v89, 0, v89, s[18:19]
	v_cndmask_b32_e64 v90, 0, v90, s[20:21]
	ds_bpermute_b32 v94, v100, v96
	v_cndmask_b32_e64 v91, 0, v91, s[22:23]
	v_cvt_pk_bf16_f32 v88, v88, v89
	v_cvt_pk_bf16_f32 v89, v90, v91
	ds_write2_b64 v110, v[92:93], v[88:89] offset1:4
	s_waitcnt lgkmcnt(0)
	s_waitcnt lgkmcnt(1)
	v_add_f32_e32 v214, v96, v94
